# weight conversion items with a norm gain: eight gain loads back to back and one wait (was load, gain load, vmcnt(0), multiply per chunk: eight serial round trips per item)
# baseline (speedup 1.0000x reference)
.LBB0_21:
	v_add_u32_e32 v6, s80, v1
	v_ashrrev_i32_e32 v7, 31, v6
	v_mul_lo_u32 v4, s86, v7
	v_mul_lo_u32 v5, s87, v6
	v_mad_u64_u32 v[2:3], s[18:19], s86, v6, 0
	v_add3_u32 v3, v3, v4, v5
	v_lshl_add_u64 v[2:3], v[2:3], 2, s[84:85]
	s_ashr_i32 s89, s88, 31
	v_lshl_add_u64 v[2:3], s[88:89], 2, v[2:3]
	v_lshlrev_b32_e32 v30, 2, v36
	v_mov_b32_e32 v31, 0
	v_lshl_add_u64 v[2:3], v[2:3], 0, v[30:31]
	global_load_dwordx4 v[2:5], v[2:3], off nt
	s_cmp_lg_u64 s[6:7], 0
	s_cselect_b64 s[52:53], -1, 0
	s_cmp_eq_u64 s[6:7], 0
	v_lshl_add_u64 v[34:35], v[6:7], 2, s[6:7]
	s_cbranch_scc1 .LBB0_23
.LBB0_23:
	v_add_u32_e32 v6, s80, v72
	v_ashrrev_i32_e32 v7, 31, v6
	v_mul_lo_u32 v8, s86, v7
	v_mul_lo_u32 v9, s87, v6
	v_mad_u64_u32 v[6:7], s[6:7], s86, v6, 0
	v_add3_u32 v7, v7, v8, v9
	v_lshl_add_u64 v[6:7], v[6:7], 2, s[84:85]
	v_lshl_add_u64 v[6:7], s[88:89], 2, v[6:7]
	v_lshl_add_u64 v[6:7], v[6:7], 0, v[30:31]
	global_load_dwordx4 v[6:9], v[6:7], off nt
	v_cndmask_b32_e64 v10, 0, 1, s[52:53]
	v_cmp_ne_u32_e64 s[6:7], 1, v10
	s_andn2_b64 vcc, exec, s[52:53]
	s_cbranch_vccnz .LBB0_25
.LBB0_25:
	v_add_u32_e32 v10, s80, v73
	v_ashrrev_i32_e32 v11, 31, v10
	v_mul_lo_u32 v12, s86, v11
	v_mul_lo_u32 v13, s87, v10
	v_mad_u64_u32 v[10:11], s[18:19], s86, v10, 0
	v_add3_u32 v11, v11, v12, v13
	v_lshl_add_u64 v[10:11], v[10:11], 2, s[84:85]
	v_lshl_add_u64 v[10:11], s[88:89], 2, v[10:11]
	v_mov_b32_e32 v31, 0
	v_lshl_add_u64 v[10:11], v[10:11], 0, v[30:31]
	global_load_dwordx4 v[10:13], v[10:11], off nt
	s_and_b64 vcc, exec, s[6:7]
	s_cbranch_vccnz .LBB0_27
.LBB0_27:
	v_add_u32_e32 v14, s80, v74
	v_ashrrev_i32_e32 v15, 31, v14
	v_mul_lo_u32 v16, s86, v15
	v_mul_lo_u32 v17, s87, v14
	v_mad_u64_u32 v[14:15], s[18:19], s86, v14, 0
	v_add3_u32 v15, v15, v16, v17
	v_lshl_add_u64 v[14:15], v[14:15], 2, s[84:85]
	v_lshl_add_u64 v[14:15], s[88:89], 2, v[14:15]
	v_lshl_add_u64 v[14:15], v[14:15], 0, v[30:31]
	global_load_dwordx4 v[14:17], v[14:15], off nt
	s_and_b64 vcc, exec, s[6:7]
	s_cbranch_vccnz .LBB0_29
.LBB0_29:
	v_add_u32_e32 v18, s80, v75
	v_ashrrev_i32_e32 v19, 31, v18
	v_mul_lo_u32 v20, s86, v19
	v_mul_lo_u32 v21, s87, v18
	v_mad_u64_u32 v[18:19], s[18:19], s86, v18, 0
	v_add3_u32 v19, v19, v20, v21
	v_lshl_add_u64 v[18:19], v[18:19], 2, s[84:85]
	v_lshl_add_u64 v[18:19], s[88:89], 2, v[18:19]
	v_mov_b32_e32 v31, 0
	v_lshl_add_u64 v[18:19], v[18:19], 0, v[30:31]
	global_load_dwordx4 v[18:21], v[18:19], off nt
	s_and_b64 vcc, exec, s[6:7]
	s_cbranch_vccnz .LBB0_31
.LBB0_31:
	v_add_u32_e32 v22, s80, v76
	v_ashrrev_i32_e32 v23, 31, v22
	v_mul_lo_u32 v24, s86, v23
	v_mul_lo_u32 v25, s87, v22
	v_mad_u64_u32 v[22:23], s[18:19], s86, v22, 0
	v_add3_u32 v23, v23, v24, v25
	v_lshl_add_u64 v[22:23], v[22:23], 2, s[84:85]
	v_lshl_add_u64 v[22:23], s[88:89], 2, v[22:23]
	v_lshl_add_u64 v[22:23], v[22:23], 0, v[30:31]
	global_load_dwordx4 v[22:25], v[22:23], off nt
	s_and_b64 vcc, exec, s[6:7]
	s_cbranch_vccnz .LBB0_33
.LBB0_33:
	v_add_u32_e32 v26, s80, v77
	v_ashrrev_i32_e32 v27, 31, v26
	v_mul_lo_u32 v28, s86, v27
	v_mul_lo_u32 v29, s87, v26
	v_mad_u64_u32 v[26:27], s[18:19], s86, v26, 0
	v_add3_u32 v27, v27, v28, v29
	v_lshl_add_u64 v[26:27], v[26:27], 2, s[84:85]
	v_lshl_add_u64 v[26:27], s[88:89], 2, v[26:27]
	v_mov_b32_e32 v31, 0
	v_lshl_add_u64 v[26:27], v[26:27], 0, v[30:31]
	global_load_dwordx4 v[26:29], v[26:27], off nt
	s_and_b64 vcc, exec, s[6:7]
	s_cbranch_vccnz .LBB0_35
.LBB0_35:
	v_add_u32_e32 v32, s80, v78
	v_ashrrev_i32_e32 v33, 31, v32
	v_mul_lo_u32 v37, s86, v33
	v_mul_lo_u32 v38, s87, v32
	v_mad_u64_u32 v[32:33], s[18:19], s86, v32, 0
	v_add3_u32 v33, v33, v37, v38
	v_lshl_add_u64 v[32:33], v[32:33], 2, s[84:85]
	v_lshl_add_u64 v[32:33], s[88:89], 2, v[32:33]
	v_lshl_add_u64 v[30:31], v[32:33], 0, v[30:31]
	global_load_dwordx4 v[30:33], v[30:31], off nt
	s_and_b64 vcc, exec, s[6:7]
	s_cbranch_vccnz .LBB0_37
	global_load_dword v90, v[34:35], off
	global_load_dword v92, v[34:35], off offset:32
	global_load_dword v94, v[34:35], off offset:64
	global_load_dword v96, v[34:35], off offset:96
	global_load_dword v98, v[34:35], off offset:128
	global_load_dword v100, v[34:35], off offset:160
	global_load_dword v102, v[34:35], off offset:192
	global_load_dword v104, v[34:35], off offset:224
	s_waitcnt vmcnt(0)
	v_pk_mul_f32 v[4:5], v[4:5], v[90:91] op_sel_hi:[1,0]
	v_pk_mul_f32 v[2:3], v[2:3], v[90:91] op_sel_hi:[1,0]
	v_pk_mul_f32 v[8:9], v[8:9], v[92:93] op_sel_hi:[1,0]
	v_pk_mul_f32 v[6:7], v[6:7], v[92:93] op_sel_hi:[1,0]
	v_pk_mul_f32 v[12:13], v[12:13], v[94:95] op_sel_hi:[1,0]
	v_pk_mul_f32 v[10:11], v[10:11], v[94:95] op_sel_hi:[1,0]
	v_pk_mul_f32 v[16:17], v[16:17], v[96:97] op_sel_hi:[1,0]
	v_pk_mul_f32 v[14:15], v[14:15], v[96:97] op_sel_hi:[1,0]
	v_pk_mul_f32 v[20:21], v[20:21], v[98:99] op_sel_hi:[1,0]
	v_pk_mul_f32 v[18:19], v[18:19], v[98:99] op_sel_hi:[1,0]
	v_pk_mul_f32 v[24:25], v[24:25], v[100:101] op_sel_hi:[1,0]
	v_pk_mul_f32 v[22:23], v[22:23], v[100:101] op_sel_hi:[1,0]
	v_pk_mul_f32 v[28:29], v[28:29], v[102:103] op_sel_hi:[1,0]
	v_pk_mul_f32 v[26:27], v[26:27], v[102:103] op_sel_hi:[1,0]
	v_pk_mul_f32 v[32:33], v[32:33], v[104:105] op_sel_hi:[1,0]
	v_pk_mul_f32 v[30:31], v[30:31], v[104:105] op_sel_hi:[1,0]

.LBB0_71:
	v_add_u32_e32 v38, s20, v1
	v_ashrrev_i32_e32 v39, 31, v38
	v_mul_lo_u32 v36, s96, v39
	v_mul_lo_u32 v37, s97, v38
	v_mad_u64_u32 v[34:35], s[22:23], s96, v38, 0
	v_add3_u32 v35, v35, v36, v37
	v_lshl_add_u64 v[34:35], v[34:35], 2, s[92:93]
	s_ashr_i32 s95, s94, 31
	v_lshl_add_u64 v[34:35], s[94:95], 2, v[34:35]
	v_lshl_add_u64 v[34:35], v[34:35], 0, v[66:67]
	global_load_dwordx4 v[34:37], v[34:35], off nt
	s_cmp_lg_u64 s[6:7], 0
	s_cselect_b64 s[52:53], -1, 0
	s_cmp_eq_u64 s[6:7], 0
	v_lshl_add_u64 v[70:71], v[38:39], 2, s[6:7]
	s_cbranch_scc1 .LBB0_73
.LBB0_73:
	v_add_u32_e32 v38, s20, v72
	v_ashrrev_i32_e32 v39, 31, v38
	v_mul_lo_u32 v40, s96, v39
	v_mul_lo_u32 v41, s97, v38
	v_mad_u64_u32 v[38:39], s[6:7], s96, v38, 0
	v_add3_u32 v39, v39, v40, v41
	v_lshl_add_u64 v[38:39], v[38:39], 2, s[92:93]
	v_lshl_add_u64 v[38:39], s[94:95], 2, v[38:39]
	v_lshl_add_u64 v[38:39], v[38:39], 0, v[66:67]
	global_load_dwordx4 v[38:41], v[38:39], off nt
	v_cndmask_b32_e64 v42, 0, 1, s[52:53]
	v_cmp_ne_u32_e64 s[6:7], 1, v42
	s_andn2_b64 vcc, exec, s[52:53]
	s_cbranch_vccnz .LBB0_75
.LBB0_75:
	v_add_u32_e32 v42, s20, v73
	v_ashrrev_i32_e32 v43, 31, v42
	v_mul_lo_u32 v44, s96, v43
	v_mul_lo_u32 v45, s97, v42
	v_mad_u64_u32 v[42:43], s[22:23], s96, v42, 0
	v_add3_u32 v43, v43, v44, v45
	v_lshl_add_u64 v[42:43], v[42:43], 2, s[92:93]
	v_lshl_add_u64 v[42:43], s[94:95], 2, v[42:43]
	v_lshl_add_u64 v[42:43], v[42:43], 0, v[66:67]
	global_load_dwordx4 v[42:45], v[42:43], off nt
	s_and_b64 vcc, exec, s[6:7]
	s_cbranch_vccnz .LBB0_77
.LBB0_77:
	v_add_u32_e32 v46, s20, v74
	v_ashrrev_i32_e32 v47, 31, v46
	v_mul_lo_u32 v48, s96, v47
	v_mul_lo_u32 v49, s97, v46
	v_mad_u64_u32 v[46:47], s[22:23], s96, v46, 0
	v_add3_u32 v47, v47, v48, v49
	v_lshl_add_u64 v[46:47], v[46:47], 2, s[92:93]
	v_lshl_add_u64 v[46:47], s[94:95], 2, v[46:47]
	v_lshl_add_u64 v[46:47], v[46:47], 0, v[66:67]
	global_load_dwordx4 v[46:49], v[46:47], off nt
	s_and_b64 vcc, exec, s[6:7]
	s_cbranch_vccnz .LBB0_79
.LBB0_79:
	v_add_u32_e32 v50, s20, v75
	v_ashrrev_i32_e32 v51, 31, v50
	v_mul_lo_u32 v52, s96, v51
	v_mul_lo_u32 v53, s97, v50
	v_mad_u64_u32 v[50:51], s[22:23], s96, v50, 0
	v_add3_u32 v51, v51, v52, v53
	v_lshl_add_u64 v[50:51], v[50:51], 2, s[92:93]
	v_lshl_add_u64 v[50:51], s[94:95], 2, v[50:51]
	v_lshl_add_u64 v[50:51], v[50:51], 0, v[66:67]
	global_load_dwordx4 v[50:53], v[50:51], off nt
	s_and_b64 vcc, exec, s[6:7]
	s_cbranch_vccnz .LBB0_81
.LBB0_81:
	v_add_u32_e32 v54, s20, v76
	v_ashrrev_i32_e32 v55, 31, v54
	v_mul_lo_u32 v56, s96, v55
	v_mul_lo_u32 v57, s97, v54
	v_mad_u64_u32 v[54:55], s[22:23], s96, v54, 0
	v_add3_u32 v55, v55, v56, v57
	v_lshl_add_u64 v[54:55], v[54:55], 2, s[92:93]
	v_lshl_add_u64 v[54:55], s[94:95], 2, v[54:55]
	v_lshl_add_u64 v[54:55], v[54:55], 0, v[66:67]
	global_load_dwordx4 v[54:57], v[54:55], off nt
	s_and_b64 vcc, exec, s[6:7]
	s_cbranch_vccnz .LBB0_83
.LBB0_83:
	v_add_u32_e32 v58, s20, v77
	v_ashrrev_i32_e32 v59, 31, v58
	v_mul_lo_u32 v60, s96, v59
	v_mul_lo_u32 v61, s97, v58
	v_mad_u64_u32 v[58:59], s[22:23], s96, v58, 0
	v_add3_u32 v59, v59, v60, v61
	v_lshl_add_u64 v[58:59], v[58:59], 2, s[92:93]
	v_lshl_add_u64 v[58:59], s[94:95], 2, v[58:59]
	v_lshl_add_u64 v[58:59], v[58:59], 0, v[66:67]
	global_load_dwordx4 v[58:61], v[58:59], off nt
	s_and_b64 vcc, exec, s[6:7]
	s_cbranch_vccnz .LBB0_85
.LBB0_85:
	v_add_u32_e32 v62, s20, v78
	v_ashrrev_i32_e32 v63, 31, v62
	v_mul_lo_u32 v64, s96, v63
	v_mul_lo_u32 v65, s97, v62
	v_mad_u64_u32 v[62:63], s[22:23], s96, v62, 0
	v_add3_u32 v63, v63, v64, v65
	v_lshl_add_u64 v[62:63], v[62:63], 2, s[92:93]
	v_lshl_add_u64 v[62:63], s[94:95], 2, v[62:63]
	v_lshl_add_u64 v[62:63], v[62:63], 0, v[66:67]
	global_load_dwordx4 v[62:65], v[62:63], off nt
	s_and_b64 vcc, exec, s[6:7]
	s_cbranch_vccnz .LBB0_40
	global_load_dword v90, v[70:71], off
	global_load_dword v92, v[70:71], off offset:32
	global_load_dword v94, v[70:71], off offset:64
	global_load_dword v96, v[70:71], off offset:96
	global_load_dword v98, v[70:71], off offset:128
	global_load_dword v100, v[70:71], off offset:160
	global_load_dword v102, v[70:71], off offset:192
	global_load_dword v104, v[70:71], off offset:224
	s_waitcnt vmcnt(0)
	v_pk_mul_f32 v[36:37], v[36:37], v[90:91] op_sel_hi:[1,0]
	v_pk_mul_f32 v[34:35], v[34:35], v[90:91] op_sel_hi:[1,0]
	v_pk_mul_f32 v[40:41], v[40:41], v[92:93] op_sel_hi:[1,0]
	v_pk_mul_f32 v[38:39], v[38:39], v[92:93] op_sel_hi:[1,0]
	v_pk_mul_f32 v[44:45], v[44:45], v[94:95] op_sel_hi:[1,0]
	v_pk_mul_f32 v[42:43], v[42:43], v[94:95] op_sel_hi:[1,0]
	v_pk_mul_f32 v[48:49], v[48:49], v[96:97] op_sel_hi:[1,0]
	v_pk_mul_f32 v[46:47], v[46:47], v[96:97] op_sel_hi:[1,0]
	v_pk_mul_f32 v[52:53], v[52:53], v[98:99] op_sel_hi:[1,0]
	v_pk_mul_f32 v[50:51], v[50:51], v[98:99] op_sel_hi:[1,0]
	v_pk_mul_f32 v[56:57], v[56:57], v[100:101] op_sel_hi:[1,0]
	v_pk_mul_f32 v[54:55], v[54:55], v[100:101] op_sel_hi:[1,0]
	v_pk_mul_f32 v[60:61], v[60:61], v[102:103] op_sel_hi:[1,0]
	v_pk_mul_f32 v[58:59], v[58:59], v[102:103] op_sel_hi:[1,0]
	v_pk_mul_f32 v[64:65], v[64:65], v[104:105] op_sel_hi:[1,0]
	v_pk_mul_f32 v[62:63], v[62:63], v[104:105] op_sel_hi:[1,0]
	s_branch .LBB0_40

.LBB0_175:
	v_lshrrev_b32_e32 v34, 3, v241
	v_add_u32_e32 v4, s74, v34
	v_lshlrev_b32_e32 v0, 2, v240
	v_ashrrev_i32_e32 v5, 31, v4
	v_and_b32_e32 v2, 28, v0
	v_mul_lo_u32 v3, s82, v5
	v_mul_lo_u32 v6, s83, v4
	v_mad_u64_u32 v[0:1], s[14:15], s82, v4, 0
	v_add3_u32 v1, v1, v3, v6
	v_lshl_add_u64 v[0:1], v[0:1], 2, s[76:77]
	s_ashr_i32 s81, s80, 31
	v_mov_b32_e32 v29, 0
	v_lshl_add_u64 v[0:1], s[80:81], 2, v[0:1]
	v_lshlrev_b32_e32 v28, 2, v2
	v_lshl_add_u64 v[0:1], v[0:1], 0, v[28:29]
	global_load_dwordx4 v[0:3], v[0:1], off nt
	s_cmp_lg_u64 s[6:7], 0
	s_cselect_b64 s[52:53], -1, 0
	s_cmp_eq_u64 s[6:7], 0
	v_lshl_add_u64 v[32:33], v[4:5], 2, s[6:7]
	s_cbranch_scc1 .LBB0_177
.LBB0_177:
	v_or_b32_e32 v35, 8, v34
	v_add_u32_e32 v4, s74, v35
	v_ashrrev_i32_e32 v5, 31, v4
	v_mul_lo_u32 v6, s82, v5
	v_mul_lo_u32 v7, s83, v4
	v_mad_u64_u32 v[4:5], s[6:7], s82, v4, 0
	v_add3_u32 v5, v5, v6, v7
	v_lshl_add_u64 v[4:5], v[4:5], 2, s[76:77]
	v_lshl_add_u64 v[4:5], s[80:81], 2, v[4:5]
	v_lshl_add_u64 v[4:5], v[4:5], 0, v[28:29]
	global_load_dwordx4 v[4:7], v[4:5], off nt
	v_cndmask_b32_e64 v8, 0, 1, s[52:53]
	v_cmp_ne_u32_e64 s[6:7], 1, v8
	s_andn2_b64 vcc, exec, s[52:53]
	s_cbranch_vccnz .LBB0_179
.LBB0_179:
	v_or_b32_e32 v36, 16, v34
	v_add_u32_e32 v8, s74, v36
	v_ashrrev_i32_e32 v9, 31, v8
	v_mul_lo_u32 v10, s82, v9
	v_mul_lo_u32 v11, s83, v8
	v_mad_u64_u32 v[8:9], s[14:15], s82, v8, 0
	v_add3_u32 v9, v9, v10, v11
	v_lshl_add_u64 v[8:9], v[8:9], 2, s[76:77]
	v_lshl_add_u64 v[8:9], s[80:81], 2, v[8:9]
	v_mov_b32_e32 v29, 0
	v_lshl_add_u64 v[8:9], v[8:9], 0, v[28:29]
	global_load_dwordx4 v[8:11], v[8:9], off nt
	s_and_b64 vcc, exec, s[6:7]
	s_cbranch_vccnz .LBB0_181
.LBB0_181:
	v_or_b32_e32 v37, 24, v34
	v_add_u32_e32 v12, s74, v37
	v_ashrrev_i32_e32 v13, 31, v12
	v_mul_lo_u32 v14, s82, v13
	v_mul_lo_u32 v15, s83, v12
	v_mad_u64_u32 v[12:13], s[14:15], s82, v12, 0
	v_add3_u32 v13, v13, v14, v15
	v_lshl_add_u64 v[12:13], v[12:13], 2, s[76:77]
	v_lshl_add_u64 v[12:13], s[80:81], 2, v[12:13]
	v_lshl_add_u64 v[12:13], v[12:13], 0, v[28:29]
	global_load_dwordx4 v[12:15], v[12:13], off nt
	s_and_b64 vcc, exec, s[6:7]
	s_cbranch_vccnz .LBB0_183
.LBB0_183:
	v_add3_u32 v16, s74, v34, 32
	v_ashrrev_i32_e32 v17, 31, v16
	v_mul_lo_u32 v18, s82, v17
	v_mul_lo_u32 v19, s83, v16
	v_mad_u64_u32 v[16:17], s[14:15], s82, v16, 0
	v_add3_u32 v17, v17, v18, v19
	v_lshl_add_u64 v[16:17], v[16:17], 2, s[76:77]
	v_lshl_add_u64 v[16:17], s[80:81], 2, v[16:17]
	v_mov_b32_e32 v29, 0
	v_lshl_add_u64 v[16:17], v[16:17], 0, v[28:29]
	global_load_dwordx4 v[16:19], v[16:17], off nt
	s_and_b64 vcc, exec, s[6:7]
	s_cbranch_vccnz .LBB0_185
.LBB0_185:
	v_add3_u32 v20, s74, v34, 40
	v_ashrrev_i32_e32 v21, 31, v20
	v_mul_lo_u32 v22, s82, v21
	v_mul_lo_u32 v23, s83, v20
	v_mad_u64_u32 v[20:21], s[14:15], s82, v20, 0
	v_add3_u32 v21, v21, v22, v23
	v_lshl_add_u64 v[20:21], v[20:21], 2, s[76:77]
	v_lshl_add_u64 v[20:21], s[80:81], 2, v[20:21]
	v_lshl_add_u64 v[20:21], v[20:21], 0, v[28:29]
	global_load_dwordx4 v[20:23], v[20:21], off nt
	s_and_b64 vcc, exec, s[6:7]
	s_cbranch_vccnz .LBB0_187
.LBB0_187:
	v_add3_u32 v24, s74, v34, 48
	v_ashrrev_i32_e32 v25, 31, v24
	v_mul_lo_u32 v26, s82, v25
	v_mul_lo_u32 v27, s83, v24
	v_mad_u64_u32 v[24:25], s[14:15], s82, v24, 0
	v_add3_u32 v25, v25, v26, v27
	v_lshl_add_u64 v[24:25], v[24:25], 2, s[76:77]
	v_lshl_add_u64 v[24:25], s[80:81], 2, v[24:25]
	v_mov_b32_e32 v29, 0
	v_lshl_add_u64 v[24:25], v[24:25], 0, v[28:29]
	global_load_dwordx4 v[24:27], v[24:25], off nt
	s_and_b64 vcc, exec, s[6:7]
	s_cbranch_vccnz .LBB0_189
.LBB0_189:
	v_add3_u32 v30, s74, v34, 56
	v_ashrrev_i32_e32 v31, 31, v30
	v_mul_lo_u32 v38, s82, v31
	v_mul_lo_u32 v39, s83, v30
	v_mad_u64_u32 v[30:31], s[14:15], s82, v30, 0
	v_add3_u32 v31, v31, v38, v39
	v_lshl_add_u64 v[30:31], v[30:31], 2, s[76:77]
	v_lshl_add_u64 v[30:31], s[80:81], 2, v[30:31]
	v_lshl_add_u64 v[28:29], v[30:31], 0, v[28:29]
	global_load_dwordx4 v[28:31], v[28:29], off nt
	s_and_b64 vcc, exec, s[6:7]
	s_cbranch_vccnz .LBB0_191
	global_load_dword v90, v[32:33], off
	global_load_dword v92, v[32:33], off offset:32
	global_load_dword v94, v[32:33], off offset:64
	global_load_dword v96, v[32:33], off offset:96
	global_load_dword v98, v[32:33], off offset:128
	global_load_dword v100, v[32:33], off offset:160
	global_load_dword v102, v[32:33], off offset:192
	global_load_dword v104, v[32:33], off offset:224
	s_waitcnt vmcnt(0)
	v_pk_mul_f32 v[2:3], v[2:3], v[90:91] op_sel_hi:[1,0]
	v_pk_mul_f32 v[0:1], v[0:1], v[90:91] op_sel_hi:[1,0]
	v_pk_mul_f32 v[6:7], v[6:7], v[92:93] op_sel_hi:[1,0]
	v_pk_mul_f32 v[4:5], v[4:5], v[92:93] op_sel_hi:[1,0]
	v_pk_mul_f32 v[10:11], v[10:11], v[94:95] op_sel_hi:[1,0]
	v_pk_mul_f32 v[8:9], v[8:9], v[94:95] op_sel_hi:[1,0]
	v_pk_mul_f32 v[14:15], v[14:15], v[96:97] op_sel_hi:[1,0]
	v_pk_mul_f32 v[12:13], v[12:13], v[96:97] op_sel_hi:[1,0]
	v_pk_mul_f32 v[18:19], v[18:19], v[98:99] op_sel_hi:[1,0]
	v_pk_mul_f32 v[16:17], v[16:17], v[98:99] op_sel_hi:[1,0]
	v_pk_mul_f32 v[22:23], v[22:23], v[100:101] op_sel_hi:[1,0]
	v_pk_mul_f32 v[20:21], v[20:21], v[100:101] op_sel_hi:[1,0]
	v_pk_mul_f32 v[26:27], v[26:27], v[102:103] op_sel_hi:[1,0]
	v_pk_mul_f32 v[24:25], v[24:25], v[102:103] op_sel_hi:[1,0]
	v_pk_mul_f32 v[30:31], v[30:31], v[104:105] op_sel_hi:[1,0]
	v_pk_mul_f32 v[28:29], v[28:29], v[104:105] op_sel_hi:[1,0]

.LBB0_338:
	v_lshrrev_b32_e32 v34, 3, v241
	v_add_u32_e32 v4, s74, v34
	v_lshlrev_b32_e32 v0, 2, v240
	v_ashrrev_i32_e32 v5, 31, v4
	v_and_b32_e32 v2, 28, v0
	v_mul_lo_u32 v3, s82, v5
	v_mul_lo_u32 v6, s83, v4
	v_mad_u64_u32 v[0:1], s[14:15], s82, v4, 0
	v_add3_u32 v1, v1, v3, v6
	v_lshl_add_u64 v[0:1], v[0:1], 2, s[76:77]
	s_ashr_i32 s81, s80, 31
	v_mov_b32_e32 v29, 0
	v_lshl_add_u64 v[0:1], s[80:81], 2, v[0:1]
	v_lshlrev_b32_e32 v28, 2, v2
	v_lshl_add_u64 v[0:1], v[0:1], 0, v[28:29]
	global_load_dwordx4 v[0:3], v[0:1], off nt
	s_cmp_lg_u64 s[6:7], 0
	s_cselect_b64 s[52:53], -1, 0
	s_cmp_eq_u64 s[6:7], 0
	v_lshl_add_u64 v[32:33], v[4:5], 2, s[6:7]
	s_cbranch_scc1 .LBB0_340
.LBB0_340:
	v_or_b32_e32 v35, 8, v34
	v_add_u32_e32 v4, s74, v35
	v_ashrrev_i32_e32 v5, 31, v4
	v_mul_lo_u32 v6, s82, v5
	v_mul_lo_u32 v7, s83, v4
	v_mad_u64_u32 v[4:5], s[6:7], s82, v4, 0
	v_add3_u32 v5, v5, v6, v7
	v_lshl_add_u64 v[4:5], v[4:5], 2, s[76:77]
	v_lshl_add_u64 v[4:5], s[80:81], 2, v[4:5]
	v_lshl_add_u64 v[4:5], v[4:5], 0, v[28:29]
	global_load_dwordx4 v[4:7], v[4:5], off nt
	v_cndmask_b32_e64 v8, 0, 1, s[52:53]
	v_cmp_ne_u32_e64 s[6:7], 1, v8
	s_andn2_b64 vcc, exec, s[52:53]
	s_cbranch_vccnz .LBB0_342
.LBB0_342:
	v_or_b32_e32 v36, 16, v34
	v_add_u32_e32 v8, s74, v36
	v_ashrrev_i32_e32 v9, 31, v8
	v_mul_lo_u32 v10, s82, v9
	v_mul_lo_u32 v11, s83, v8
	v_mad_u64_u32 v[8:9], s[14:15], s82, v8, 0
	v_add3_u32 v9, v9, v10, v11
	v_lshl_add_u64 v[8:9], v[8:9], 2, s[76:77]
	v_lshl_add_u64 v[8:9], s[80:81], 2, v[8:9]
	v_mov_b32_e32 v29, 0
	v_lshl_add_u64 v[8:9], v[8:9], 0, v[28:29]
	global_load_dwordx4 v[8:11], v[8:9], off nt
	s_and_b64 vcc, exec, s[6:7]
	s_cbranch_vccnz .LBB0_344
.LBB0_344:
	v_or_b32_e32 v37, 24, v34
	v_add_u32_e32 v12, s74, v37
	v_ashrrev_i32_e32 v13, 31, v12
	v_mul_lo_u32 v14, s82, v13
	v_mul_lo_u32 v15, s83, v12
	v_mad_u64_u32 v[12:13], s[14:15], s82, v12, 0
	v_add3_u32 v13, v13, v14, v15
	v_lshl_add_u64 v[12:13], v[12:13], 2, s[76:77]
	v_lshl_add_u64 v[12:13], s[80:81], 2, v[12:13]
	v_lshl_add_u64 v[12:13], v[12:13], 0, v[28:29]
	global_load_dwordx4 v[12:15], v[12:13], off nt
	s_and_b64 vcc, exec, s[6:7]
	s_cbranch_vccnz .LBB0_346
.LBB0_346:
	v_add3_u32 v16, s74, v34, 32
	v_ashrrev_i32_e32 v17, 31, v16
	v_mul_lo_u32 v18, s82, v17
	v_mul_lo_u32 v19, s83, v16
	v_mad_u64_u32 v[16:17], s[14:15], s82, v16, 0
	v_add3_u32 v17, v17, v18, v19
	v_lshl_add_u64 v[16:17], v[16:17], 2, s[76:77]
	v_lshl_add_u64 v[16:17], s[80:81], 2, v[16:17]
	v_mov_b32_e32 v29, 0
	v_lshl_add_u64 v[16:17], v[16:17], 0, v[28:29]
	global_load_dwordx4 v[16:19], v[16:17], off nt
	s_and_b64 vcc, exec, s[6:7]
	s_cbranch_vccnz .LBB0_348
.LBB0_348:
	v_add3_u32 v20, s74, v34, 40
	v_ashrrev_i32_e32 v21, 31, v20
	v_mul_lo_u32 v22, s82, v21
	v_mul_lo_u32 v23, s83, v20
	v_mad_u64_u32 v[20:21], s[14:15], s82, v20, 0
	v_add3_u32 v21, v21, v22, v23
	v_lshl_add_u64 v[20:21], v[20:21], 2, s[76:77]
	v_lshl_add_u64 v[20:21], s[80:81], 2, v[20:21]
	v_lshl_add_u64 v[20:21], v[20:21], 0, v[28:29]
	global_load_dwordx4 v[20:23], v[20:21], off nt
	s_and_b64 vcc, exec, s[6:7]
	s_cbranch_vccnz .LBB0_350
.LBB0_350:
	v_add3_u32 v24, s74, v34, 48
	v_ashrrev_i32_e32 v25, 31, v24
	v_mul_lo_u32 v26, s82, v25
	v_mul_lo_u32 v27, s83, v24
	v_mad_u64_u32 v[24:25], s[14:15], s82, v24, 0
	v_add3_u32 v25, v25, v26, v27
	v_lshl_add_u64 v[24:25], v[24:25], 2, s[76:77]
	v_lshl_add_u64 v[24:25], s[80:81], 2, v[24:25]
	v_mov_b32_e32 v29, 0
	v_lshl_add_u64 v[24:25], v[24:25], 0, v[28:29]
	global_load_dwordx4 v[24:27], v[24:25], off nt
	s_and_b64 vcc, exec, s[6:7]
	s_cbranch_vccnz .LBB0_352

.LBB0_508:
	v_lshrrev_b32_e32 v34, 3, v241
	v_add_u32_e32 v4, s42, v34
	v_lshlrev_b32_e32 v0, 2, v240
	v_ashrrev_i32_e32 v5, 31, v4
	v_and_b32_e32 v2, 28, v0
	v_mul_lo_u32 v3, s82, v5
	v_mul_lo_u32 v6, s83, v4
	v_mad_u64_u32 v[0:1], s[14:15], s82, v4, 0
	v_add3_u32 v1, v1, v3, v6
	v_lshl_add_u64 v[0:1], v[0:1], 2, s[76:77]
	s_ashr_i32 s81, s80, 31
	v_mov_b32_e32 v29, 0
	v_lshl_add_u64 v[0:1], s[80:81], 2, v[0:1]
	v_lshlrev_b32_e32 v28, 2, v2
	v_lshl_add_u64 v[0:1], v[0:1], 0, v[28:29]
	global_load_dwordx4 v[0:3], v[0:1], off nt
	s_cmp_lg_u64 s[6:7], 0
	s_cselect_b64 s[52:53], -1, 0
	s_cmp_eq_u64 s[6:7], 0
	v_lshl_add_u64 v[32:33], v[4:5], 2, s[6:7]
	s_cbranch_scc1 .LBB0_510
.LBB0_510:
	v_or_b32_e32 v35, 8, v34
	v_add_u32_e32 v4, s42, v35
	v_ashrrev_i32_e32 v5, 31, v4
	v_mul_lo_u32 v6, s82, v5
	v_mul_lo_u32 v7, s83, v4
	v_mad_u64_u32 v[4:5], s[6:7], s82, v4, 0
	v_add3_u32 v5, v5, v6, v7
	v_lshl_add_u64 v[4:5], v[4:5], 2, s[76:77]
	v_lshl_add_u64 v[4:5], s[80:81], 2, v[4:5]
	v_lshl_add_u64 v[4:5], v[4:5], 0, v[28:29]
	global_load_dwordx4 v[4:7], v[4:5], off nt
	v_cndmask_b32_e64 v8, 0, 1, s[52:53]
	v_cmp_ne_u32_e64 s[6:7], 1, v8
	s_andn2_b64 vcc, exec, s[52:53]
	s_cbranch_vccnz .LBB0_512
.LBB0_512:
	v_or_b32_e32 v36, 16, v34
	v_add_u32_e32 v8, s42, v36
	v_ashrrev_i32_e32 v9, 31, v8
	v_mul_lo_u32 v10, s82, v9
	v_mul_lo_u32 v11, s83, v8
	v_mad_u64_u32 v[8:9], s[14:15], s82, v8, 0
	v_add3_u32 v9, v9, v10, v11
	v_lshl_add_u64 v[8:9], v[8:9], 2, s[76:77]
	v_lshl_add_u64 v[8:9], s[80:81], 2, v[8:9]
	v_mov_b32_e32 v29, 0
	v_lshl_add_u64 v[8:9], v[8:9], 0, v[28:29]
	global_load_dwordx4 v[8:11], v[8:9], off nt
	s_and_b64 vcc, exec, s[6:7]
	s_cbranch_vccnz .LBB0_514
.LBB0_514:
	v_or_b32_e32 v37, 24, v34
	v_add_u32_e32 v12, s42, v37
	v_ashrrev_i32_e32 v13, 31, v12
	v_mul_lo_u32 v14, s82, v13
	v_mul_lo_u32 v15, s83, v12
	v_mad_u64_u32 v[12:13], s[14:15], s82, v12, 0
	v_add3_u32 v13, v13, v14, v15
	v_lshl_add_u64 v[12:13], v[12:13], 2, s[76:77]
	v_lshl_add_u64 v[12:13], s[80:81], 2, v[12:13]
	v_lshl_add_u64 v[12:13], v[12:13], 0, v[28:29]
	global_load_dwordx4 v[12:15], v[12:13], off nt
	s_and_b64 vcc, exec, s[6:7]
	s_cbranch_vccnz .LBB0_516
.LBB0_516:
	v_add3_u32 v16, s42, v34, 32
	v_ashrrev_i32_e32 v17, 31, v16
	v_mul_lo_u32 v18, s82, v17
	v_mul_lo_u32 v19, s83, v16
	v_mad_u64_u32 v[16:17], s[14:15], s82, v16, 0
	v_add3_u32 v17, v17, v18, v19
	v_lshl_add_u64 v[16:17], v[16:17], 2, s[76:77]
	v_lshl_add_u64 v[16:17], s[80:81], 2, v[16:17]
	v_mov_b32_e32 v29, 0
	v_lshl_add_u64 v[16:17], v[16:17], 0, v[28:29]
	global_load_dwordx4 v[16:19], v[16:17], off nt
	s_and_b64 vcc, exec, s[6:7]
	s_cbranch_vccnz .LBB0_518
.LBB0_518:
	v_add3_u32 v20, s42, v34, 40
	v_ashrrev_i32_e32 v21, 31, v20
	v_mul_lo_u32 v22, s82, v21
	v_mul_lo_u32 v23, s83, v20
	v_mad_u64_u32 v[20:21], s[14:15], s82, v20, 0
	v_add3_u32 v21, v21, v22, v23
	v_lshl_add_u64 v[20:21], v[20:21], 2, s[76:77]
	v_lshl_add_u64 v[20:21], s[80:81], 2, v[20:21]
	v_lshl_add_u64 v[20:21], v[20:21], 0, v[28:29]
	global_load_dwordx4 v[20:23], v[20:21], off nt
	s_and_b64 vcc, exec, s[6:7]
	s_cbranch_vccnz .LBB0_520
.LBB0_520:
	v_add3_u32 v24, s42, v34, 48
	v_ashrrev_i32_e32 v25, 31, v24
	v_mul_lo_u32 v26, s82, v25
	v_mul_lo_u32 v27, s83, v24
	v_mad_u64_u32 v[24:25], s[14:15], s82, v24, 0
	v_add3_u32 v25, v25, v26, v27
	v_lshl_add_u64 v[24:25], v[24:25], 2, s[76:77]
	v_lshl_add_u64 v[24:25], s[80:81], 2, v[24:25]
	v_mov_b32_e32 v29, 0
	v_lshl_add_u64 v[24:25], v[24:25], 0, v[28:29]
	global_load_dwordx4 v[24:27], v[24:25], off nt
	s_and_b64 vcc, exec, s[6:7]
	s_cbranch_vccnz .LBB0_522
.LBB0_522:
	v_add3_u32 v30, s42, v34, 56
	v_ashrrev_i32_e32 v31, 31, v30
	v_mul_lo_u32 v38, s82, v31
	v_mul_lo_u32 v39, s83, v30
	v_mad_u64_u32 v[30:31], s[14:15], s82, v30, 0
	v_add3_u32 v31, v31, v38, v39
	v_lshl_add_u64 v[30:31], v[30:31], 2, s[76:77]
	v_lshl_add_u64 v[30:31], s[80:81], 2, v[30:31]
	v_lshl_add_u64 v[28:29], v[30:31], 0, v[28:29]
	global_load_dwordx4 v[28:31], v[28:29], off nt
	s_and_b64 vcc, exec, s[6:7]
	s_cbranch_vccnz .LBB0_524
	global_load_dword v90, v[32:33], off
	global_load_dword v92, v[32:33], off offset:32
	global_load_dword v94, v[32:33], off offset:64
	global_load_dword v96, v[32:33], off offset:96
	global_load_dword v98, v[32:33], off offset:128
	global_load_dword v100, v[32:33], off offset:160
	global_load_dword v102, v[32:33], off offset:192
	global_load_dword v104, v[32:33], off offset:224
	s_waitcnt vmcnt(0)
	v_pk_mul_f32 v[2:3], v[2:3], v[90:91] op_sel_hi:[1,0]
	v_pk_mul_f32 v[0:1], v[0:1], v[90:91] op_sel_hi:[1,0]
	v_pk_mul_f32 v[6:7], v[6:7], v[92:93] op_sel_hi:[1,0]
	v_pk_mul_f32 v[4:5], v[4:5], v[92:93] op_sel_hi:[1,0]
	v_pk_mul_f32 v[10:11], v[10:11], v[94:95] op_sel_hi:[1,0]
	v_pk_mul_f32 v[8:9], v[8:9], v[94:95] op_sel_hi:[1,0]
	v_pk_mul_f32 v[14:15], v[14:15], v[96:97] op_sel_hi:[1,0]
	v_pk_mul_f32 v[12:13], v[12:13], v[96:97] op_sel_hi:[1,0]
	v_pk_mul_f32 v[18:19], v[18:19], v[98:99] op_sel_hi:[1,0]
	v_pk_mul_f32 v[16:17], v[16:17], v[98:99] op_sel_hi:[1,0]
	v_pk_mul_f32 v[22:23], v[22:23], v[100:101] op_sel_hi:[1,0]
	v_pk_mul_f32 v[20:21], v[20:21], v[100:101] op_sel_hi:[1,0]
	v_pk_mul_f32 v[26:27], v[26:27], v[102:103] op_sel_hi:[1,0]
	v_pk_mul_f32 v[24:25], v[24:25], v[102:103] op_sel_hi:[1,0]
	v_pk_mul_f32 v[30:31], v[30:31], v[104:105] op_sel_hi:[1,0]
	v_pk_mul_f32 v[28:29], v[28:29], v[104:105] op_sel_hi:[1,0]

.LBB0_684:
	v_lshrrev_b32_e32 v34, 3, v241
	v_add_u32_e32 v4, s10, v34
	v_lshlrev_b32_e32 v0, 2, v240
	v_ashrrev_i32_e32 v5, 31, v4
	v_and_b32_e32 v2, 28, v0
	v_mul_lo_u32 v3, s76, v5
	v_mul_lo_u32 v6, s77, v4
	v_mad_u64_u32 v[0:1], s[14:15], s76, v4, 0
	v_add3_u32 v1, v1, v3, v6
	v_lshl_add_u64 v[0:1], v[0:1], 2, s[44:45]
	s_ashr_i32 s49, s48, 31
	v_mov_b32_e32 v29, 0
	v_lshl_add_u64 v[0:1], s[48:49], 2, v[0:1]
	v_lshlrev_b32_e32 v28, 2, v2
	v_lshl_add_u64 v[0:1], v[0:1], 0, v[28:29]
	global_load_dwordx4 v[0:3], v[0:1], off nt
	s_cmp_lg_u64 s[4:5], 0
	s_cselect_b64 s[52:53], -1, 0
	s_cmp_eq_u64 s[4:5], 0
	v_lshl_add_u64 v[32:33], v[4:5], 2, s[4:5]
	s_cbranch_scc1 .LBB0_686
.LBB0_686:
	v_or_b32_e32 v35, 8, v34
	v_add_u32_e32 v4, s10, v35
	v_ashrrev_i32_e32 v5, 31, v4
	v_mul_lo_u32 v6, s76, v5
	v_mul_lo_u32 v7, s77, v4
	v_mad_u64_u32 v[4:5], s[4:5], s76, v4, 0
	v_add3_u32 v5, v5, v6, v7
	v_lshl_add_u64 v[4:5], v[4:5], 2, s[44:45]
	v_lshl_add_u64 v[4:5], s[48:49], 2, v[4:5]
	v_lshl_add_u64 v[4:5], v[4:5], 0, v[28:29]
	global_load_dwordx4 v[4:7], v[4:5], off nt
	v_cndmask_b32_e64 v8, 0, 1, s[52:53]
	v_cmp_ne_u32_e64 s[4:5], 1, v8
	s_andn2_b64 vcc, exec, s[52:53]
	s_cbranch_vccnz .LBB0_688
.LBB0_688:
	v_or_b32_e32 v36, 16, v34
	v_add_u32_e32 v8, s10, v36
	v_ashrrev_i32_e32 v9, 31, v8
	v_mul_lo_u32 v10, s76, v9
	v_mul_lo_u32 v11, s77, v8
	v_mad_u64_u32 v[8:9], s[14:15], s76, v8, 0
	v_add3_u32 v9, v9, v10, v11
	v_lshl_add_u64 v[8:9], v[8:9], 2, s[44:45]
	v_lshl_add_u64 v[8:9], s[48:49], 2, v[8:9]
	v_mov_b32_e32 v29, 0
	v_lshl_add_u64 v[8:9], v[8:9], 0, v[28:29]
	global_load_dwordx4 v[8:11], v[8:9], off nt
	s_and_b64 vcc, exec, s[4:5]
	s_cbranch_vccnz .LBB0_690
.LBB0_690:
	v_or_b32_e32 v37, 24, v34
	v_add_u32_e32 v12, s10, v37
	v_ashrrev_i32_e32 v13, 31, v12
	v_mul_lo_u32 v14, s76, v13
	v_mul_lo_u32 v15, s77, v12
	v_mad_u64_u32 v[12:13], s[14:15], s76, v12, 0
	v_add3_u32 v13, v13, v14, v15
	v_lshl_add_u64 v[12:13], v[12:13], 2, s[44:45]
	v_lshl_add_u64 v[12:13], s[48:49], 2, v[12:13]
	v_lshl_add_u64 v[12:13], v[12:13], 0, v[28:29]
	global_load_dwordx4 v[12:15], v[12:13], off nt
	s_and_b64 vcc, exec, s[4:5]
	s_cbranch_vccnz .LBB0_692
.LBB0_692:
	v_add3_u32 v16, s10, v34, 32
	v_ashrrev_i32_e32 v17, 31, v16
	v_mul_lo_u32 v18, s76, v17
	v_mul_lo_u32 v19, s77, v16
	v_mad_u64_u32 v[16:17], s[14:15], s76, v16, 0
	v_add3_u32 v17, v17, v18, v19
	v_lshl_add_u64 v[16:17], v[16:17], 2, s[44:45]
	v_lshl_add_u64 v[16:17], s[48:49], 2, v[16:17]
	v_mov_b32_e32 v29, 0
	v_lshl_add_u64 v[16:17], v[16:17], 0, v[28:29]
	global_load_dwordx4 v[16:19], v[16:17], off nt
	s_and_b64 vcc, exec, s[4:5]
	s_cbranch_vccnz .LBB0_694
.LBB0_694:
	v_add3_u32 v20, s10, v34, 40
	v_ashrrev_i32_e32 v21, 31, v20
	v_mul_lo_u32 v22, s76, v21
	v_mul_lo_u32 v23, s77, v20
	v_mad_u64_u32 v[20:21], s[14:15], s76, v20, 0
	v_add3_u32 v21, v21, v22, v23
	v_lshl_add_u64 v[20:21], v[20:21], 2, s[44:45]
	v_lshl_add_u64 v[20:21], s[48:49], 2, v[20:21]
	v_lshl_add_u64 v[20:21], v[20:21], 0, v[28:29]
	global_load_dwordx4 v[20:23], v[20:21], off nt
	s_and_b64 vcc, exec, s[4:5]
	s_cbranch_vccnz .LBB0_696
.LBB0_696:
	v_add3_u32 v24, s10, v34, 48
	v_ashrrev_i32_e32 v25, 31, v24
	v_mul_lo_u32 v26, s76, v25
	v_mul_lo_u32 v27, s77, v24
	v_mad_u64_u32 v[24:25], s[14:15], s76, v24, 0
	v_add3_u32 v25, v25, v26, v27
	v_lshl_add_u64 v[24:25], v[24:25], 2, s[44:45]
	v_lshl_add_u64 v[24:25], s[48:49], 2, v[24:25]
	v_mov_b32_e32 v29, 0
	v_lshl_add_u64 v[24:25], v[24:25], 0, v[28:29]
	global_load_dwordx4 v[24:27], v[24:25], off nt
	s_and_b64 vcc, exec, s[4:5]
	s_cbranch_vccnz .LBB0_698
.LBB0_698:
	v_add3_u32 v30, s10, v34, 56
	v_ashrrev_i32_e32 v31, 31, v30
	v_mul_lo_u32 v38, s76, v31
	v_mul_lo_u32 v39, s77, v30
	v_mad_u64_u32 v[30:31], s[14:15], s76, v30, 0
	v_add3_u32 v31, v31, v38, v39
	v_lshl_add_u64 v[30:31], v[30:31], 2, s[44:45]
	v_lshl_add_u64 v[30:31], s[48:49], 2, v[30:31]
	v_lshl_add_u64 v[28:29], v[30:31], 0, v[28:29]
	global_load_dwordx4 v[28:31], v[28:29], off nt
	s_and_b64 vcc, exec, s[4:5]
	s_cbranch_vccnz .LBB0_700
	global_load_dword v90, v[32:33], off
	global_load_dword v92, v[32:33], off offset:32
	global_load_dword v94, v[32:33], off offset:64
	global_load_dword v96, v[32:33], off offset:96
	global_load_dword v98, v[32:33], off offset:128
	global_load_dword v100, v[32:33], off offset:160
	global_load_dword v102, v[32:33], off offset:192
	global_load_dword v104, v[32:33], off offset:224
	s_waitcnt vmcnt(0)
	v_pk_mul_f32 v[2:3], v[2:3], v[90:91] op_sel_hi:[1,0]
	v_pk_mul_f32 v[0:1], v[0:1], v[90:91] op_sel_hi:[1,0]
	v_pk_mul_f32 v[6:7], v[6:7], v[92:93] op_sel_hi:[1,0]
	v_pk_mul_f32 v[4:5], v[4:5], v[92:93] op_sel_hi:[1,0]
	v_pk_mul_f32 v[10:11], v[10:11], v[94:95] op_sel_hi:[1,0]
	v_pk_mul_f32 v[8:9], v[8:9], v[94:95] op_sel_hi:[1,0]
	v_pk_mul_f32 v[14:15], v[14:15], v[96:97] op_sel_hi:[1,0]
	v_pk_mul_f32 v[12:13], v[12:13], v[96:97] op_sel_hi:[1,0]
	v_pk_mul_f32 v[18:19], v[18:19], v[98:99] op_sel_hi:[1,0]
	v_pk_mul_f32 v[16:17], v[16:17], v[98:99] op_sel_hi:[1,0]
	v_pk_mul_f32 v[22:23], v[22:23], v[100:101] op_sel_hi:[1,0]
	v_pk_mul_f32 v[20:21], v[20:21], v[100:101] op_sel_hi:[1,0]
	v_pk_mul_f32 v[26:27], v[26:27], v[102:103] op_sel_hi:[1,0]
	v_pk_mul_f32 v[24:25], v[24:25], v[102:103] op_sel_hi:[1,0]
	v_pk_mul_f32 v[30:31], v[30:31], v[104:105] op_sel_hi:[1,0]
	v_pk_mul_f32 v[28:29], v[28:29], v[104:105] op_sel_hi:[1,0]

.LBB0_900:
	v_lshrrev_b32_e32 v34, 3, v241
	v_add_u32_e32 v4, s10, v34
	v_lshlrev_b32_e32 v0, 2, v240
	v_ashrrev_i32_e32 v5, 31, v4
	v_and_b32_e32 v2, 28, v0
	v_mul_lo_u32 v3, s50, v5
	v_mul_lo_u32 v6, s51, v4
	v_mad_u64_u32 v[0:1], s[14:15], s50, v4, 0
	v_add3_u32 v1, v1, v3, v6
	v_lshl_add_u64 v[0:1], v[0:1], 2, s[44:45]
	s_ashr_i32 s49, s48, 31
	v_mov_b32_e32 v29, 0
	v_lshl_add_u64 v[0:1], s[48:49], 2, v[0:1]
	v_lshlrev_b32_e32 v28, 2, v2
	v_lshl_add_u64 v[0:1], v[0:1], 0, v[28:29]
	global_load_dwordx4 v[0:3], v[0:1], off nt
	s_cmp_lg_u64 s[4:5], 0
	s_cselect_b64 s[52:53], -1, 0
	s_cmp_eq_u64 s[4:5], 0
	v_lshl_add_u64 v[32:33], v[4:5], 2, s[4:5]
	s_cbranch_scc1 .LBB0_902
.LBB0_902:
	v_or_b32_e32 v35, 8, v34
	v_add_u32_e32 v4, s10, v35
	v_ashrrev_i32_e32 v5, 31, v4
	v_mul_lo_u32 v6, s50, v5
	v_mul_lo_u32 v7, s51, v4
	v_mad_u64_u32 v[4:5], s[4:5], s50, v4, 0
	v_add3_u32 v5, v5, v6, v7
	v_lshl_add_u64 v[4:5], v[4:5], 2, s[44:45]
	v_lshl_add_u64 v[4:5], s[48:49], 2, v[4:5]
	v_lshl_add_u64 v[4:5], v[4:5], 0, v[28:29]
	global_load_dwordx4 v[4:7], v[4:5], off nt
	v_cndmask_b32_e64 v8, 0, 1, s[52:53]
	v_cmp_ne_u32_e64 s[4:5], 1, v8
	s_andn2_b64 vcc, exec, s[52:53]
	s_cbranch_vccnz .LBB0_904
.LBB0_904:
	v_or_b32_e32 v36, 16, v34
	v_add_u32_e32 v8, s10, v36
	v_ashrrev_i32_e32 v9, 31, v8
	v_mul_lo_u32 v10, s50, v9
	v_mul_lo_u32 v11, s51, v8
	v_mad_u64_u32 v[8:9], s[14:15], s50, v8, 0
	v_add3_u32 v9, v9, v10, v11
	v_lshl_add_u64 v[8:9], v[8:9], 2, s[44:45]
	v_lshl_add_u64 v[8:9], s[48:49], 2, v[8:9]
	v_mov_b32_e32 v29, 0
	v_lshl_add_u64 v[8:9], v[8:9], 0, v[28:29]
	global_load_dwordx4 v[8:11], v[8:9], off nt
	s_and_b64 vcc, exec, s[4:5]
	s_cbranch_vccnz .LBB0_906
.LBB0_906:
	v_or_b32_e32 v37, 24, v34
	v_add_u32_e32 v12, s10, v37
	v_ashrrev_i32_e32 v13, 31, v12
	v_mul_lo_u32 v14, s50, v13
	v_mul_lo_u32 v15, s51, v12
	v_mad_u64_u32 v[12:13], s[14:15], s50, v12, 0
	v_add3_u32 v13, v13, v14, v15
	v_lshl_add_u64 v[12:13], v[12:13], 2, s[44:45]
	v_lshl_add_u64 v[12:13], s[48:49], 2, v[12:13]
	v_lshl_add_u64 v[12:13], v[12:13], 0, v[28:29]
	global_load_dwordx4 v[12:15], v[12:13], off nt
	s_and_b64 vcc, exec, s[4:5]
	s_cbranch_vccnz .LBB0_908
.LBB0_908:
	v_add3_u32 v16, s10, v34, 32
	v_ashrrev_i32_e32 v17, 31, v16
	v_mul_lo_u32 v18, s50, v17
	v_mul_lo_u32 v19, s51, v16
	v_mad_u64_u32 v[16:17], s[14:15], s50, v16, 0
	v_add3_u32 v17, v17, v18, v19
	v_lshl_add_u64 v[16:17], v[16:17], 2, s[44:45]
	v_lshl_add_u64 v[16:17], s[48:49], 2, v[16:17]
	v_mov_b32_e32 v29, 0
	v_lshl_add_u64 v[16:17], v[16:17], 0, v[28:29]
	global_load_dwordx4 v[16:19], v[16:17], off nt
	s_and_b64 vcc, exec, s[4:5]
	s_cbranch_vccnz .LBB0_910
.LBB0_910:
	v_add3_u32 v20, s10, v34, 40
	v_ashrrev_i32_e32 v21, 31, v20
	v_mul_lo_u32 v22, s50, v21
	v_mul_lo_u32 v23, s51, v20
	v_mad_u64_u32 v[20:21], s[14:15], s50, v20, 0
	v_add3_u32 v21, v21, v22, v23
	v_lshl_add_u64 v[20:21], v[20:21], 2, s[44:45]
	v_lshl_add_u64 v[20:21], s[48:49], 2, v[20:21]
	v_lshl_add_u64 v[20:21], v[20:21], 0, v[28:29]
	global_load_dwordx4 v[20:23], v[20:21], off nt
	s_and_b64 vcc, exec, s[4:5]
	s_cbranch_vccnz .LBB0_912
.LBB0_912:
	v_add3_u32 v24, s10, v34, 48
	v_ashrrev_i32_e32 v25, 31, v24
	v_mul_lo_u32 v26, s50, v25
	v_mul_lo_u32 v27, s51, v24
	v_mad_u64_u32 v[24:25], s[14:15], s50, v24, 0
	v_add3_u32 v25, v25, v26, v27
	v_lshl_add_u64 v[24:25], v[24:25], 2, s[44:45]
	v_lshl_add_u64 v[24:25], s[48:49], 2, v[24:25]
	v_mov_b32_e32 v29, 0
	v_lshl_add_u64 v[24:25], v[24:25], 0, v[28:29]
	global_load_dwordx4 v[24:27], v[24:25], off nt
	s_and_b64 vcc, exec, s[4:5]
	s_cbranch_vccnz .LBB0_914
.LBB0_914:
	v_add3_u32 v30, s10, v34, 56
	v_ashrrev_i32_e32 v31, 31, v30
	v_mul_lo_u32 v38, s50, v31
	v_mul_lo_u32 v39, s51, v30
	v_mad_u64_u32 v[30:31], s[14:15], s50, v30, 0
	v_add3_u32 v31, v31, v38, v39
	v_lshl_add_u64 v[30:31], v[30:31], 2, s[44:45]
	v_lshl_add_u64 v[30:31], s[48:49], 2, v[30:31]
	v_lshl_add_u64 v[28:29], v[30:31], 0, v[28:29]
	global_load_dwordx4 v[28:31], v[28:29], off nt
	s_and_b64 vcc, exec, s[4:5]
	s_cbranch_vccnz .LBB0_916
	global_load_dword v90, v[32:33], off
	global_load_dword v92, v[32:33], off offset:32
	global_load_dword v94, v[32:33], off offset:64
	global_load_dword v96, v[32:33], off offset:96
	global_load_dword v98, v[32:33], off offset:128
	global_load_dword v100, v[32:33], off offset:160
	global_load_dword v102, v[32:33], off offset:192
	global_load_dword v104, v[32:33], off offset:224
	s_waitcnt vmcnt(0)
	v_pk_mul_f32 v[2:3], v[2:3], v[90:91] op_sel_hi:[1,0]
	v_pk_mul_f32 v[0:1], v[0:1], v[90:91] op_sel_hi:[1,0]
	v_pk_mul_f32 v[6:7], v[6:7], v[92:93] op_sel_hi:[1,0]
	v_pk_mul_f32 v[4:5], v[4:5], v[92:93] op_sel_hi:[1,0]
	v_pk_mul_f32 v[10:11], v[10:11], v[94:95] op_sel_hi:[1,0]
	v_pk_mul_f32 v[8:9], v[8:9], v[94:95] op_sel_hi:[1,0]
	v_pk_mul_f32 v[14:15], v[14:15], v[96:97] op_sel_hi:[1,0]
	v_pk_mul_f32 v[12:13], v[12:13], v[96:97] op_sel_hi:[1,0]
	v_pk_mul_f32 v[18:19], v[18:19], v[98:99] op_sel_hi:[1,0]
	v_pk_mul_f32 v[16:17], v[16:17], v[98:99] op_sel_hi:[1,0]
	v_pk_mul_f32 v[22:23], v[22:23], v[100:101] op_sel_hi:[1,0]
	v_pk_mul_f32 v[20:21], v[20:21], v[100:101] op_sel_hi:[1,0]
	v_pk_mul_f32 v[26:27], v[26:27], v[102:103] op_sel_hi:[1,0]
	v_pk_mul_f32 v[24:25], v[24:25], v[102:103] op_sel_hi:[1,0]
	v_pk_mul_f32 v[30:31], v[30:31], v[104:105] op_sel_hi:[1,0]
	v_pk_mul_f32 v[28:29], v[28:29], v[104:105] op_sel_hi:[1,0]

.LBB0_1059:
	v_lshrrev_b32_e32 v34, 3, v241
	v_add_u32_e32 v4, s10, v34
	v_lshlrev_b32_e32 v0, 2, v240
	v_ashrrev_i32_e32 v5, 31, v4
	v_and_b32_e32 v2, 28, v0
	v_mul_lo_u32 v3, s50, v5
	v_mul_lo_u32 v6, s51, v4
	v_mad_u64_u32 v[0:1], s[14:15], s50, v4, 0
	v_add3_u32 v1, v1, v3, v6
	v_lshl_add_u64 v[0:1], v[0:1], 2, s[44:45]
	s_ashr_i32 s49, s48, 31
	v_mov_b32_e32 v29, 0
	v_lshl_add_u64 v[0:1], s[48:49], 2, v[0:1]
	v_lshlrev_b32_e32 v28, 2, v2
	v_lshl_add_u64 v[0:1], v[0:1], 0, v[28:29]
	global_load_dwordx4 v[0:3], v[0:1], off nt
	s_cmp_lg_u64 s[4:5], 0
	s_cselect_b64 s[52:53], -1, 0
	s_cmp_eq_u64 s[4:5], 0
	v_lshl_add_u64 v[32:33], v[4:5], 2, s[4:5]
	s_cbranch_scc1 .LBB0_1061
.LBB0_1061:
	v_or_b32_e32 v35, 8, v34
	v_add_u32_e32 v4, s10, v35
	v_ashrrev_i32_e32 v5, 31, v4
	v_mul_lo_u32 v6, s50, v5
	v_mul_lo_u32 v7, s51, v4
	v_mad_u64_u32 v[4:5], s[4:5], s50, v4, 0
	v_add3_u32 v5, v5, v6, v7
	v_lshl_add_u64 v[4:5], v[4:5], 2, s[44:45]
	v_lshl_add_u64 v[4:5], s[48:49], 2, v[4:5]
	v_lshl_add_u64 v[4:5], v[4:5], 0, v[28:29]
	global_load_dwordx4 v[4:7], v[4:5], off nt
	v_cndmask_b32_e64 v8, 0, 1, s[52:53]
	v_cmp_ne_u32_e64 s[4:5], 1, v8
	s_andn2_b64 vcc, exec, s[52:53]
	s_cbranch_vccnz .LBB0_1063
.LBB0_1063:
	v_or_b32_e32 v36, 16, v34
	v_add_u32_e32 v8, s10, v36
	v_ashrrev_i32_e32 v9, 31, v8
	v_mul_lo_u32 v10, s50, v9
	v_mul_lo_u32 v11, s51, v8
	v_mad_u64_u32 v[8:9], s[14:15], s50, v8, 0
	v_add3_u32 v9, v9, v10, v11
	v_lshl_add_u64 v[8:9], v[8:9], 2, s[44:45]
	v_lshl_add_u64 v[8:9], s[48:49], 2, v[8:9]
	v_mov_b32_e32 v29, 0
	v_lshl_add_u64 v[8:9], v[8:9], 0, v[28:29]
	global_load_dwordx4 v[8:11], v[8:9], off nt
	s_and_b64 vcc, exec, s[4:5]
	s_cbranch_vccnz .LBB0_1065
.LBB0_1065:
	v_or_b32_e32 v37, 24, v34
	v_add_u32_e32 v12, s10, v37
	v_ashrrev_i32_e32 v13, 31, v12
	v_mul_lo_u32 v14, s50, v13
	v_mul_lo_u32 v15, s51, v12
	v_mad_u64_u32 v[12:13], s[14:15], s50, v12, 0
	v_add3_u32 v13, v13, v14, v15
	v_lshl_add_u64 v[12:13], v[12:13], 2, s[44:45]
	v_lshl_add_u64 v[12:13], s[48:49], 2, v[12:13]
	v_lshl_add_u64 v[12:13], v[12:13], 0, v[28:29]
	global_load_dwordx4 v[12:15], v[12:13], off nt
	s_and_b64 vcc, exec, s[4:5]
	s_cbranch_vccnz .LBB0_1067
.LBB0_1067:
	v_add3_u32 v16, s10, v34, 32
	v_ashrrev_i32_e32 v17, 31, v16
	v_mul_lo_u32 v18, s50, v17
	v_mul_lo_u32 v19, s51, v16
	v_mad_u64_u32 v[16:17], s[14:15], s50, v16, 0
	v_add3_u32 v17, v17, v18, v19
	v_lshl_add_u64 v[16:17], v[16:17], 2, s[44:45]
	v_lshl_add_u64 v[16:17], s[48:49], 2, v[16:17]
	v_mov_b32_e32 v29, 0
	v_lshl_add_u64 v[16:17], v[16:17], 0, v[28:29]
	global_load_dwordx4 v[16:19], v[16:17], off nt
	s_and_b64 vcc, exec, s[4:5]
	s_cbranch_vccnz .LBB0_1069
.LBB0_1069:
	v_add3_u32 v20, s10, v34, 40
	v_ashrrev_i32_e32 v21, 31, v20
	v_mul_lo_u32 v22, s50, v21
	v_mul_lo_u32 v23, s51, v20
	v_mad_u64_u32 v[20:21], s[14:15], s50, v20, 0
	v_add3_u32 v21, v21, v22, v23
	v_lshl_add_u64 v[20:21], v[20:21], 2, s[44:45]
	v_lshl_add_u64 v[20:21], s[48:49], 2, v[20:21]
	v_lshl_add_u64 v[20:21], v[20:21], 0, v[28:29]
	global_load_dwordx4 v[20:23], v[20:21], off nt
	s_and_b64 vcc, exec, s[4:5]
	s_cbranch_vccnz .LBB0_1071
.LBB0_1071:
	v_add3_u32 v24, s10, v34, 48
	v_ashrrev_i32_e32 v25, 31, v24
	v_mul_lo_u32 v26, s50, v25
	v_mul_lo_u32 v27, s51, v24
	v_mad_u64_u32 v[24:25], s[14:15], s50, v24, 0
	v_add3_u32 v25, v25, v26, v27
	v_lshl_add_u64 v[24:25], v[24:25], 2, s[44:45]
	v_lshl_add_u64 v[24:25], s[48:49], 2, v[24:25]
	v_mov_b32_e32 v29, 0
	v_lshl_add_u64 v[24:25], v[24:25], 0, v[28:29]
	global_load_dwordx4 v[24:27], v[24:25], off nt
	s_and_b64 vcc, exec, s[4:5]
	s_cbranch_vccnz .LBB0_1073

.LBB0_1202:
	v_lshrrev_b32_e32 v34, 3, v241
	v_add_u32_e32 v4, s10, v34
	v_lshlrev_b32_e32 v0, 2, v240
	v_ashrrev_i32_e32 v5, 31, v4
	v_and_b32_e32 v2, 28, v0
	v_mul_lo_u32 v3, s50, v5
	v_mul_lo_u32 v6, s51, v4
	v_mad_u64_u32 v[0:1], s[14:15], s50, v4, 0
	v_add3_u32 v1, v1, v3, v6
	v_lshl_add_u64 v[0:1], v[0:1], 2, s[44:45]
	s_ashr_i32 s49, s48, 31
	v_mov_b32_e32 v29, 0
	v_lshl_add_u64 v[0:1], s[48:49], 2, v[0:1]
	v_lshlrev_b32_e32 v28, 2, v2
	v_lshl_add_u64 v[0:1], v[0:1], 0, v[28:29]
	global_load_dwordx4 v[0:3], v[0:1], off nt
	s_cmp_lg_u64 s[4:5], 0
	s_cselect_b64 s[52:53], -1, 0
	s_cmp_eq_u64 s[4:5], 0
	v_lshl_add_u64 v[32:33], v[4:5], 2, s[4:5]
	s_cbranch_scc1 .LBB0_1204
.LBB0_1204:
	v_or_b32_e32 v35, 8, v34
	v_add_u32_e32 v4, s10, v35
	v_ashrrev_i32_e32 v5, 31, v4
	v_mul_lo_u32 v6, s50, v5
	v_mul_lo_u32 v7, s51, v4
	v_mad_u64_u32 v[4:5], s[4:5], s50, v4, 0
	v_add3_u32 v5, v5, v6, v7
	v_lshl_add_u64 v[4:5], v[4:5], 2, s[44:45]
	v_lshl_add_u64 v[4:5], s[48:49], 2, v[4:5]
	v_lshl_add_u64 v[4:5], v[4:5], 0, v[28:29]
	global_load_dwordx4 v[4:7], v[4:5], off nt
	v_cndmask_b32_e64 v8, 0, 1, s[52:53]
	v_cmp_ne_u32_e64 s[4:5], 1, v8
	s_andn2_b64 vcc, exec, s[52:53]
	s_cbranch_vccnz .LBB0_1206
.LBB0_1206:
	v_or_b32_e32 v36, 16, v34
	v_add_u32_e32 v8, s10, v36
	v_ashrrev_i32_e32 v9, 31, v8
	v_mul_lo_u32 v10, s50, v9
	v_mul_lo_u32 v11, s51, v8
	v_mad_u64_u32 v[8:9], s[14:15], s50, v8, 0
	v_add3_u32 v9, v9, v10, v11
	v_lshl_add_u64 v[8:9], v[8:9], 2, s[44:45]
	v_lshl_add_u64 v[8:9], s[48:49], 2, v[8:9]
	v_mov_b32_e32 v29, 0
	v_lshl_add_u64 v[8:9], v[8:9], 0, v[28:29]
	global_load_dwordx4 v[8:11], v[8:9], off nt
	s_and_b64 vcc, exec, s[4:5]
	s_cbranch_vccnz .LBB0_1208
.LBB0_1208:
	v_or_b32_e32 v37, 24, v34
	v_add_u32_e32 v12, s10, v37
	v_ashrrev_i32_e32 v13, 31, v12
	v_mul_lo_u32 v14, s50, v13
	v_mul_lo_u32 v15, s51, v12
	v_mad_u64_u32 v[12:13], s[14:15], s50, v12, 0
	v_add3_u32 v13, v13, v14, v15
	v_lshl_add_u64 v[12:13], v[12:13], 2, s[44:45]
	v_lshl_add_u64 v[12:13], s[48:49], 2, v[12:13]
	v_lshl_add_u64 v[12:13], v[12:13], 0, v[28:29]
	global_load_dwordx4 v[12:15], v[12:13], off nt
	s_and_b64 vcc, exec, s[4:5]
	s_cbranch_vccnz .LBB0_1210
.LBB0_1210:
	v_add3_u32 v16, s10, v34, 32
	v_ashrrev_i32_e32 v17, 31, v16
	v_mul_lo_u32 v18, s50, v17
	v_mul_lo_u32 v19, s51, v16
	v_mad_u64_u32 v[16:17], s[14:15], s50, v16, 0
	v_add3_u32 v17, v17, v18, v19
	v_lshl_add_u64 v[16:17], v[16:17], 2, s[44:45]
	v_lshl_add_u64 v[16:17], s[48:49], 2, v[16:17]
	v_mov_b32_e32 v29, 0
	v_lshl_add_u64 v[16:17], v[16:17], 0, v[28:29]
	global_load_dwordx4 v[16:19], v[16:17], off nt
	s_and_b64 vcc, exec, s[4:5]
	s_cbranch_vccnz .LBB0_1212
.LBB0_1212:
	v_add3_u32 v20, s10, v34, 40
	v_ashrrev_i32_e32 v21, 31, v20
	v_mul_lo_u32 v22, s50, v21
	v_mul_lo_u32 v23, s51, v20
	v_mad_u64_u32 v[20:21], s[14:15], s50, v20, 0
	v_add3_u32 v21, v21, v22, v23
	v_lshl_add_u64 v[20:21], v[20:21], 2, s[44:45]
	v_lshl_add_u64 v[20:21], s[48:49], 2, v[20:21]
	v_lshl_add_u64 v[20:21], v[20:21], 0, v[28:29]
	global_load_dwordx4 v[20:23], v[20:21], off nt
	s_and_b64 vcc, exec, s[4:5]
	s_cbranch_vccnz .LBB0_1214
.LBB0_1214:
	v_add3_u32 v24, s10, v34, 48
	v_ashrrev_i32_e32 v25, 31, v24
	v_mul_lo_u32 v26, s50, v25
	v_mul_lo_u32 v27, s51, v24
	v_mad_u64_u32 v[24:25], s[14:15], s50, v24, 0
	v_add3_u32 v25, v25, v26, v27
	v_lshl_add_u64 v[24:25], v[24:25], 2, s[44:45]
	v_lshl_add_u64 v[24:25], s[48:49], 2, v[24:25]
	v_mov_b32_e32 v29, 0
	v_lshl_add_u64 v[24:25], v[24:25], 0, v[28:29]
	global_load_dwordx4 v[24:27], v[24:25], off nt
	s_and_b64 vcc, exec, s[4:5]
	s_cbranch_vccnz .LBB0_1216

.LBB0_1365:
	v_lshrrev_b32_e32 v34, 3, v241
	v_add_u32_e32 v4, s10, v34
	v_lshlrev_b32_e32 v0, 2, v240
	v_ashrrev_i32_e32 v5, 31, v4
	v_and_b32_e32 v2, 28, v0
	v_mul_lo_u32 v3, s50, v5
	v_mul_lo_u32 v6, s51, v4
	v_mad_u64_u32 v[0:1], s[14:15], s50, v4, 0
	v_add3_u32 v1, v1, v3, v6
	v_lshl_add_u64 v[0:1], v[0:1], 2, s[44:45]
	s_ashr_i32 s49, s48, 31
	v_mov_b32_e32 v29, 0
	v_lshl_add_u64 v[0:1], s[48:49], 2, v[0:1]
	v_lshlrev_b32_e32 v28, 2, v2
	v_lshl_add_u64 v[0:1], v[0:1], 0, v[28:29]
	global_load_dwordx4 v[0:3], v[0:1], off nt
	s_cmp_lg_u64 s[4:5], 0
	s_cselect_b64 s[52:53], -1, 0
	s_cmp_eq_u64 s[4:5], 0
	v_lshl_add_u64 v[32:33], v[4:5], 2, s[4:5]
	s_cbranch_scc1 .LBB0_1367
.LBB0_1367:
	v_or_b32_e32 v35, 8, v34
	v_add_u32_e32 v4, s10, v35
	v_ashrrev_i32_e32 v5, 31, v4
	v_mul_lo_u32 v6, s50, v5
	v_mul_lo_u32 v7, s51, v4
	v_mad_u64_u32 v[4:5], s[4:5], s50, v4, 0
	v_add3_u32 v5, v5, v6, v7
	v_lshl_add_u64 v[4:5], v[4:5], 2, s[44:45]
	v_lshl_add_u64 v[4:5], s[48:49], 2, v[4:5]
	v_lshl_add_u64 v[4:5], v[4:5], 0, v[28:29]
	global_load_dwordx4 v[4:7], v[4:5], off nt
	v_cndmask_b32_e64 v8, 0, 1, s[52:53]
	v_cmp_ne_u32_e64 s[4:5], 1, v8
	s_andn2_b64 vcc, exec, s[52:53]
	s_cbranch_vccnz .LBB0_1369
.LBB0_1369:
	v_or_b32_e32 v36, 16, v34
	v_add_u32_e32 v8, s10, v36
	v_ashrrev_i32_e32 v9, 31, v8
	v_mul_lo_u32 v10, s50, v9
	v_mul_lo_u32 v11, s51, v8
	v_mad_u64_u32 v[8:9], s[14:15], s50, v8, 0
	v_add3_u32 v9, v9, v10, v11
	v_lshl_add_u64 v[8:9], v[8:9], 2, s[44:45]
	v_lshl_add_u64 v[8:9], s[48:49], 2, v[8:9]
	v_mov_b32_e32 v29, 0
	v_lshl_add_u64 v[8:9], v[8:9], 0, v[28:29]
	global_load_dwordx4 v[8:11], v[8:9], off nt
	s_and_b64 vcc, exec, s[4:5]
	s_cbranch_vccnz .LBB0_1371
.LBB0_1371:
	v_or_b32_e32 v37, 24, v34
	v_add_u32_e32 v12, s10, v37
	v_ashrrev_i32_e32 v13, 31, v12
	v_mul_lo_u32 v14, s50, v13
	v_mul_lo_u32 v15, s51, v12
	v_mad_u64_u32 v[12:13], s[14:15], s50, v12, 0
	v_add3_u32 v13, v13, v14, v15
	v_lshl_add_u64 v[12:13], v[12:13], 2, s[44:45]
	v_lshl_add_u64 v[12:13], s[48:49], 2, v[12:13]
	v_lshl_add_u64 v[12:13], v[12:13], 0, v[28:29]
	global_load_dwordx4 v[12:15], v[12:13], off nt
	s_and_b64 vcc, exec, s[4:5]
	s_cbranch_vccnz .LBB0_1373
.LBB0_1373:
	v_add3_u32 v16, s10, v34, 32
	v_ashrrev_i32_e32 v17, 31, v16
	v_mul_lo_u32 v18, s50, v17
	v_mul_lo_u32 v19, s51, v16
	v_mad_u64_u32 v[16:17], s[14:15], s50, v16, 0
	v_add3_u32 v17, v17, v18, v19
	v_lshl_add_u64 v[16:17], v[16:17], 2, s[44:45]
	v_lshl_add_u64 v[16:17], s[48:49], 2, v[16:17]
	v_mov_b32_e32 v29, 0
	v_lshl_add_u64 v[16:17], v[16:17], 0, v[28:29]
	global_load_dwordx4 v[16:19], v[16:17], off nt
	s_and_b64 vcc, exec, s[4:5]
	s_cbranch_vccnz .LBB0_1375
.LBB0_1375:
	v_add3_u32 v20, s10, v34, 40
	v_ashrrev_i32_e32 v21, 31, v20
	v_mul_lo_u32 v22, s50, v21
	v_mul_lo_u32 v23, s51, v20
	v_mad_u64_u32 v[20:21], s[14:15], s50, v20, 0
	v_add3_u32 v21, v21, v22, v23
	v_lshl_add_u64 v[20:21], v[20:21], 2, s[44:45]
	v_lshl_add_u64 v[20:21], s[48:49], 2, v[20:21]
	v_lshl_add_u64 v[20:21], v[20:21], 0, v[28:29]
	global_load_dwordx4 v[20:23], v[20:21], off nt
	s_and_b64 vcc, exec, s[4:5]
	s_cbranch_vccnz .LBB0_1377
.LBB0_1377:
	v_add3_u32 v24, s10, v34, 48
	v_ashrrev_i32_e32 v25, 31, v24
	v_mul_lo_u32 v26, s50, v25
	v_mul_lo_u32 v27, s51, v24
	v_mad_u64_u32 v[24:25], s[14:15], s50, v24, 0
	v_add3_u32 v25, v25, v26, v27
	v_lshl_add_u64 v[24:25], v[24:25], 2, s[44:45]
	v_lshl_add_u64 v[24:25], s[48:49], 2, v[24:25]
	v_mov_b32_e32 v29, 0
	v_lshl_add_u64 v[24:25], v[24:25], 0, v[28:29]
	global_load_dwordx4 v[24:27], v[24:25], off nt
	s_and_b64 vcc, exec, s[4:5]
	s_cbranch_vccnz .LBB0_1379

.LBB0_1508:
	v_lshrrev_b32_e32 v34, 3, v241
	v_add_u32_e32 v4, s10, v34
	v_lshlrev_b32_e32 v0, 2, v240
	v_ashrrev_i32_e32 v5, 31, v4
	v_and_b32_e32 v2, 28, v0
	v_mul_lo_u32 v3, s50, v5
	v_mul_lo_u32 v6, s51, v4
	v_mad_u64_u32 v[0:1], s[14:15], s50, v4, 0
	v_add3_u32 v1, v1, v3, v6
	v_lshl_add_u64 v[0:1], v[0:1], 2, s[44:45]
	s_ashr_i32 s49, s48, 31
	v_mov_b32_e32 v29, 0
	v_lshl_add_u64 v[0:1], s[48:49], 2, v[0:1]
	v_lshlrev_b32_e32 v28, 2, v2
	v_lshl_add_u64 v[0:1], v[0:1], 0, v[28:29]
	global_load_dwordx4 v[0:3], v[0:1], off nt
	s_cmp_lg_u64 s[4:5], 0
	s_cselect_b64 s[52:53], -1, 0
	s_cmp_eq_u64 s[4:5], 0
	v_lshl_add_u64 v[32:33], v[4:5], 2, s[4:5]
	s_cbranch_scc1 .LBB0_1510
.LBB0_1510:
	v_or_b32_e32 v35, 8, v34
	v_add_u32_e32 v4, s10, v35
	v_ashrrev_i32_e32 v5, 31, v4
	v_mul_lo_u32 v6, s50, v5
	v_mul_lo_u32 v7, s51, v4
	v_mad_u64_u32 v[4:5], s[4:5], s50, v4, 0
	v_add3_u32 v5, v5, v6, v7
	v_lshl_add_u64 v[4:5], v[4:5], 2, s[44:45]
	v_lshl_add_u64 v[4:5], s[48:49], 2, v[4:5]
	v_lshl_add_u64 v[4:5], v[4:5], 0, v[28:29]
	global_load_dwordx4 v[4:7], v[4:5], off nt
	v_cndmask_b32_e64 v8, 0, 1, s[52:53]
	v_cmp_ne_u32_e64 s[4:5], 1, v8
	s_andn2_b64 vcc, exec, s[52:53]
	s_cbranch_vccnz .LBB0_1512
.LBB0_1512:
	v_or_b32_e32 v36, 16, v34
	v_add_u32_e32 v8, s10, v36
	v_ashrrev_i32_e32 v9, 31, v8
	v_mul_lo_u32 v10, s50, v9
	v_mul_lo_u32 v11, s51, v8
	v_mad_u64_u32 v[8:9], s[14:15], s50, v8, 0
	v_add3_u32 v9, v9, v10, v11
	v_lshl_add_u64 v[8:9], v[8:9], 2, s[44:45]
	v_lshl_add_u64 v[8:9], s[48:49], 2, v[8:9]
	v_mov_b32_e32 v29, 0
	v_lshl_add_u64 v[8:9], v[8:9], 0, v[28:29]
	global_load_dwordx4 v[8:11], v[8:9], off nt
	s_and_b64 vcc, exec, s[4:5]
	s_cbranch_vccnz .LBB0_1514
.LBB0_1514:
	v_or_b32_e32 v37, 24, v34
	v_add_u32_e32 v12, s10, v37
	v_ashrrev_i32_e32 v13, 31, v12
	v_mul_lo_u32 v14, s50, v13
	v_mul_lo_u32 v15, s51, v12
	v_mad_u64_u32 v[12:13], s[14:15], s50, v12, 0
	v_add3_u32 v13, v13, v14, v15
	v_lshl_add_u64 v[12:13], v[12:13], 2, s[44:45]
	v_lshl_add_u64 v[12:13], s[48:49], 2, v[12:13]
	v_lshl_add_u64 v[12:13], v[12:13], 0, v[28:29]
	global_load_dwordx4 v[12:15], v[12:13], off nt
	s_and_b64 vcc, exec, s[4:5]
	s_cbranch_vccnz .LBB0_1516
.LBB0_1516:
	v_add3_u32 v16, s10, v34, 32
	v_ashrrev_i32_e32 v17, 31, v16
	v_mul_lo_u32 v18, s50, v17
	v_mul_lo_u32 v19, s51, v16
	v_mad_u64_u32 v[16:17], s[14:15], s50, v16, 0
	v_add3_u32 v17, v17, v18, v19
	v_lshl_add_u64 v[16:17], v[16:17], 2, s[44:45]
	v_lshl_add_u64 v[16:17], s[48:49], 2, v[16:17]
	v_mov_b32_e32 v29, 0
	v_lshl_add_u64 v[16:17], v[16:17], 0, v[28:29]
	global_load_dwordx4 v[16:19], v[16:17], off nt
	s_and_b64 vcc, exec, s[4:5]
	s_cbranch_vccnz .LBB0_1518
.LBB0_1518:
	v_add3_u32 v20, s10, v34, 40
	v_ashrrev_i32_e32 v21, 31, v20
	v_mul_lo_u32 v22, s50, v21
	v_mul_lo_u32 v23, s51, v20
	v_mad_u64_u32 v[20:21], s[14:15], s50, v20, 0
	v_add3_u32 v21, v21, v22, v23
	v_lshl_add_u64 v[20:21], v[20:21], 2, s[44:45]
	v_lshl_add_u64 v[20:21], s[48:49], 2, v[20:21]
	v_lshl_add_u64 v[20:21], v[20:21], 0, v[28:29]
	global_load_dwordx4 v[20:23], v[20:21], off nt
	s_and_b64 vcc, exec, s[4:5]
	s_cbranch_vccnz .LBB0_1520
.LBB0_1520:
	v_add3_u32 v24, s10, v34, 48
	v_ashrrev_i32_e32 v25, 31, v24
	v_mul_lo_u32 v26, s50, v25
	v_mul_lo_u32 v27, s51, v24
	v_mad_u64_u32 v[24:25], s[14:15], s50, v24, 0
	v_add3_u32 v25, v25, v26, v27
	v_lshl_add_u64 v[24:25], v[24:25], 2, s[44:45]
	v_lshl_add_u64 v[24:25], s[48:49], 2, v[24:25]
	v_mov_b32_e32 v29, 0
	v_lshl_add_u64 v[24:25], v[24:25], 0, v[28:29]
	global_load_dwordx4 v[24:27], v[24:25], off nt
	s_and_b64 vcc, exec, s[4:5]
	s_cbranch_vccnz .LBB0_1522

.LBB0_1671:
	v_lshrrev_b32_e32 v34, 3, v241
	v_add_u32_e32 v4, s10, v34
	v_lshlrev_b32_e32 v0, 2, v240
	v_ashrrev_i32_e32 v5, 31, v4
	v_and_b32_e32 v2, 28, v0
	v_mul_lo_u32 v3, s50, v5
	v_mul_lo_u32 v6, s51, v4
	v_mad_u64_u32 v[0:1], s[14:15], s50, v4, 0
	v_add3_u32 v1, v1, v3, v6
	v_lshl_add_u64 v[0:1], v[0:1], 2, s[44:45]
	s_ashr_i32 s49, s48, 31
	v_mov_b32_e32 v29, 0
	v_lshl_add_u64 v[0:1], s[48:49], 2, v[0:1]
	v_lshlrev_b32_e32 v28, 2, v2
	v_lshl_add_u64 v[0:1], v[0:1], 0, v[28:29]
	global_load_dwordx4 v[0:3], v[0:1], off nt
	s_cmp_lg_u64 s[4:5], 0
	s_cselect_b64 s[52:53], -1, 0
	s_cmp_eq_u64 s[4:5], 0
	v_lshl_add_u64 v[32:33], v[4:5], 2, s[4:5]
	s_cbranch_scc1 .LBB0_1673
.LBB0_1673:
	v_or_b32_e32 v35, 8, v34
	v_add_u32_e32 v4, s10, v35
	v_ashrrev_i32_e32 v5, 31, v4
	v_mul_lo_u32 v6, s50, v5
	v_mul_lo_u32 v7, s51, v4
	v_mad_u64_u32 v[4:5], s[4:5], s50, v4, 0
	v_add3_u32 v5, v5, v6, v7
	v_lshl_add_u64 v[4:5], v[4:5], 2, s[44:45]
	v_lshl_add_u64 v[4:5], s[48:49], 2, v[4:5]
	v_lshl_add_u64 v[4:5], v[4:5], 0, v[28:29]
	global_load_dwordx4 v[4:7], v[4:5], off nt
	v_cndmask_b32_e64 v8, 0, 1, s[52:53]
	v_cmp_ne_u32_e64 s[4:5], 1, v8
	s_andn2_b64 vcc, exec, s[52:53]
	s_cbranch_vccnz .LBB0_1675
.LBB0_1675:
	v_or_b32_e32 v36, 16, v34
	v_add_u32_e32 v8, s10, v36
	v_ashrrev_i32_e32 v9, 31, v8
	v_mul_lo_u32 v10, s50, v9
	v_mul_lo_u32 v11, s51, v8
	v_mad_u64_u32 v[8:9], s[14:15], s50, v8, 0
	v_add3_u32 v9, v9, v10, v11
	v_lshl_add_u64 v[8:9], v[8:9], 2, s[44:45]
	v_lshl_add_u64 v[8:9], s[48:49], 2, v[8:9]
	v_mov_b32_e32 v29, 0
	v_lshl_add_u64 v[8:9], v[8:9], 0, v[28:29]
	global_load_dwordx4 v[8:11], v[8:9], off nt
	s_and_b64 vcc, exec, s[4:5]
	s_cbranch_vccnz .LBB0_1677
.LBB0_1677:
	v_or_b32_e32 v37, 24, v34
	v_add_u32_e32 v12, s10, v37
	v_ashrrev_i32_e32 v13, 31, v12
	v_mul_lo_u32 v14, s50, v13
	v_mul_lo_u32 v15, s51, v12
	v_mad_u64_u32 v[12:13], s[14:15], s50, v12, 0
	v_add3_u32 v13, v13, v14, v15
	v_lshl_add_u64 v[12:13], v[12:13], 2, s[44:45]
	v_lshl_add_u64 v[12:13], s[48:49], 2, v[12:13]
	v_lshl_add_u64 v[12:13], v[12:13], 0, v[28:29]
	global_load_dwordx4 v[12:15], v[12:13], off nt
	s_and_b64 vcc, exec, s[4:5]
	s_cbranch_vccnz .LBB0_1679
.LBB0_1679:
	v_add3_u32 v16, s10, v34, 32
	v_ashrrev_i32_e32 v17, 31, v16
	v_mul_lo_u32 v18, s50, v17
	v_mul_lo_u32 v19, s51, v16
	v_mad_u64_u32 v[16:17], s[14:15], s50, v16, 0
	v_add3_u32 v17, v17, v18, v19
	v_lshl_add_u64 v[16:17], v[16:17], 2, s[44:45]
	v_lshl_add_u64 v[16:17], s[48:49], 2, v[16:17]
	v_mov_b32_e32 v29, 0
	v_lshl_add_u64 v[16:17], v[16:17], 0, v[28:29]
	global_load_dwordx4 v[16:19], v[16:17], off nt
	s_and_b64 vcc, exec, s[4:5]
	s_cbranch_vccnz .LBB0_1681
.LBB0_1681:
	v_add3_u32 v20, s10, v34, 40
	v_ashrrev_i32_e32 v21, 31, v20
	v_mul_lo_u32 v22, s50, v21
	v_mul_lo_u32 v23, s51, v20
	v_mad_u64_u32 v[20:21], s[14:15], s50, v20, 0
	v_add3_u32 v21, v21, v22, v23
	v_lshl_add_u64 v[20:21], v[20:21], 2, s[44:45]
	v_lshl_add_u64 v[20:21], s[48:49], 2, v[20:21]
	v_lshl_add_u64 v[20:21], v[20:21], 0, v[28:29]
	global_load_dwordx4 v[20:23], v[20:21], off nt
	s_and_b64 vcc, exec, s[4:5]
	s_cbranch_vccnz .LBB0_1683
.LBB0_1683:
	v_add3_u32 v24, s10, v34, 48
	v_ashrrev_i32_e32 v25, 31, v24
	v_mul_lo_u32 v26, s50, v25
	v_mul_lo_u32 v27, s51, v24
	v_mad_u64_u32 v[24:25], s[14:15], s50, v24, 0
	v_add3_u32 v25, v25, v26, v27
	v_lshl_add_u64 v[24:25], v[24:25], 2, s[44:45]
	v_lshl_add_u64 v[24:25], s[48:49], 2, v[24:25]
	v_mov_b32_e32 v29, 0
	v_lshl_add_u64 v[24:25], v[24:25], 0, v[28:29]
	global_load_dwordx4 v[24:27], v[24:25], off nt
	s_and_b64 vcc, exec, s[4:5]
	s_cbranch_vccnz .LBB0_1685

.LBB0_1818:
	v_lshrrev_b32_e32 v34, 3, v241
	v_add_u32_e32 v4, s10, v34
	v_lshlrev_b32_e32 v0, 2, v240
	v_ashrrev_i32_e32 v5, 31, v4
	v_and_b32_e32 v2, 28, v0
	v_mul_lo_u32 v3, s50, v5
	v_mul_lo_u32 v6, s51, v4
	v_mad_u64_u32 v[0:1], s[14:15], s50, v4, 0
	v_add3_u32 v1, v1, v3, v6
	v_lshl_add_u64 v[0:1], v[0:1], 2, s[44:45]
	s_ashr_i32 s49, s48, 31
	v_mov_b32_e32 v29, 0
	v_lshl_add_u64 v[0:1], s[48:49], 2, v[0:1]
	v_lshlrev_b32_e32 v28, 2, v2
	v_lshl_add_u64 v[0:1], v[0:1], 0, v[28:29]
	global_load_dwordx4 v[0:3], v[0:1], off nt
	s_cmp_lg_u64 s[4:5], 0
	s_cselect_b64 s[52:53], -1, 0
	s_cmp_eq_u64 s[4:5], 0
	v_lshl_add_u64 v[32:33], v[4:5], 2, s[4:5]
	s_cbranch_scc1 .LBB0_1820
.LBB0_1820:
	v_or_b32_e32 v35, 8, v34
	v_add_u32_e32 v4, s10, v35
	v_ashrrev_i32_e32 v5, 31, v4
	v_mul_lo_u32 v6, s50, v5
	v_mul_lo_u32 v7, s51, v4
	v_mad_u64_u32 v[4:5], s[4:5], s50, v4, 0
	v_add3_u32 v5, v5, v6, v7
	v_lshl_add_u64 v[4:5], v[4:5], 2, s[44:45]
	v_lshl_add_u64 v[4:5], s[48:49], 2, v[4:5]
	v_lshl_add_u64 v[4:5], v[4:5], 0, v[28:29]
	global_load_dwordx4 v[4:7], v[4:5], off nt
	v_cndmask_b32_e64 v8, 0, 1, s[52:53]
	v_cmp_ne_u32_e64 s[4:5], 1, v8
	s_andn2_b64 vcc, exec, s[52:53]
	s_cbranch_vccnz .LBB0_1822
.LBB0_1822:
	v_or_b32_e32 v36, 16, v34
	v_add_u32_e32 v8, s10, v36
	v_ashrrev_i32_e32 v9, 31, v8
	v_mul_lo_u32 v10, s50, v9
	v_mul_lo_u32 v11, s51, v8
	v_mad_u64_u32 v[8:9], s[14:15], s50, v8, 0
	v_add3_u32 v9, v9, v10, v11
	v_lshl_add_u64 v[8:9], v[8:9], 2, s[44:45]
	v_lshl_add_u64 v[8:9], s[48:49], 2, v[8:9]
	v_mov_b32_e32 v29, 0
	v_lshl_add_u64 v[8:9], v[8:9], 0, v[28:29]
	global_load_dwordx4 v[8:11], v[8:9], off nt
	s_and_b64 vcc, exec, s[4:5]
	s_cbranch_vccnz .LBB0_1824
.LBB0_1824:
	v_or_b32_e32 v37, 24, v34
	v_add_u32_e32 v12, s10, v37
	v_ashrrev_i32_e32 v13, 31, v12
	v_mul_lo_u32 v14, s50, v13
	v_mul_lo_u32 v15, s51, v12
	v_mad_u64_u32 v[12:13], s[14:15], s50, v12, 0
	v_add3_u32 v13, v13, v14, v15
	v_lshl_add_u64 v[12:13], v[12:13], 2, s[44:45]
	v_lshl_add_u64 v[12:13], s[48:49], 2, v[12:13]
	v_lshl_add_u64 v[12:13], v[12:13], 0, v[28:29]
	global_load_dwordx4 v[12:15], v[12:13], off nt
	s_and_b64 vcc, exec, s[4:5]
	s_cbranch_vccnz .LBB0_1826
.LBB0_1826:
	v_add3_u32 v16, s10, v34, 32
	v_ashrrev_i32_e32 v17, 31, v16
	v_mul_lo_u32 v18, s50, v17
	v_mul_lo_u32 v19, s51, v16
	v_mad_u64_u32 v[16:17], s[14:15], s50, v16, 0
	v_add3_u32 v17, v17, v18, v19
	v_lshl_add_u64 v[16:17], v[16:17], 2, s[44:45]
	v_lshl_add_u64 v[16:17], s[48:49], 2, v[16:17]
	v_mov_b32_e32 v29, 0
	v_lshl_add_u64 v[16:17], v[16:17], 0, v[28:29]
	global_load_dwordx4 v[16:19], v[16:17], off nt
	s_and_b64 vcc, exec, s[4:5]
	s_cbranch_vccnz .LBB0_1828
.LBB0_1828:
	v_add3_u32 v20, s10, v34, 40
	v_ashrrev_i32_e32 v21, 31, v20
	v_mul_lo_u32 v22, s50, v21
	v_mul_lo_u32 v23, s51, v20
	v_mad_u64_u32 v[20:21], s[14:15], s50, v20, 0
	v_add3_u32 v21, v21, v22, v23
	v_lshl_add_u64 v[20:21], v[20:21], 2, s[44:45]
	v_lshl_add_u64 v[20:21], s[48:49], 2, v[20:21]
	v_lshl_add_u64 v[20:21], v[20:21], 0, v[28:29]
	global_load_dwordx4 v[20:23], v[20:21], off nt
	s_and_b64 vcc, exec, s[4:5]
	s_cbranch_vccnz .LBB0_1830
.LBB0_1830:
	v_add3_u32 v24, s10, v34, 48
	v_ashrrev_i32_e32 v25, 31, v24
	v_mul_lo_u32 v26, s50, v25
	v_mul_lo_u32 v27, s51, v24
	v_mad_u64_u32 v[24:25], s[14:15], s50, v24, 0
	v_add3_u32 v25, v25, v26, v27
	v_lshl_add_u64 v[24:25], v[24:25], 2, s[44:45]
	v_lshl_add_u64 v[24:25], s[48:49], 2, v[24:25]
	v_mov_b32_e32 v29, 0
	v_lshl_add_u64 v[24:25], v[24:25], 0, v[28:29]
	global_load_dwordx4 v[24:27], v[24:25], off nt
	s_and_b64 vcc, exec, s[4:5]
	s_cbranch_vccnz .LBB0_1832

.LBB0_1944:
	v_lshrrev_b32_e32 v34, 3, v241
	v_add_u32_e32 v4, s10, v34
	v_lshlrev_b32_e32 v0, 2, v240
	v_ashrrev_i32_e32 v5, 31, v4
	v_and_b32_e32 v2, 28, v0
	v_mul_lo_u32 v3, s50, v5
	v_mul_lo_u32 v6, s51, v4
	v_mad_u64_u32 v[0:1], s[14:15], s50, v4, 0
	v_add3_u32 v1, v1, v3, v6
	v_lshl_add_u64 v[0:1], v[0:1], 2, s[44:45]
	s_ashr_i32 s49, s48, 31
	v_mov_b32_e32 v29, 0
	v_lshl_add_u64 v[0:1], s[48:49], 2, v[0:1]
	v_lshlrev_b32_e32 v28, 2, v2
	v_lshl_add_u64 v[0:1], v[0:1], 0, v[28:29]
	global_load_dwordx4 v[0:3], v[0:1], off nt
	s_cmp_lg_u64 s[4:5], 0
	s_cselect_b64 s[52:53], -1, 0
	s_cmp_eq_u64 s[4:5], 0
	v_lshl_add_u64 v[32:33], v[4:5], 2, s[4:5]
	s_cbranch_scc1 .LBB0_1946
.LBB0_1946:
	v_or_b32_e32 v35, 8, v34
	v_add_u32_e32 v4, s10, v35
	v_ashrrev_i32_e32 v5, 31, v4
	v_mul_lo_u32 v6, s50, v5
	v_mul_lo_u32 v7, s51, v4
	v_mad_u64_u32 v[4:5], s[4:5], s50, v4, 0
	v_add3_u32 v5, v5, v6, v7
	v_lshl_add_u64 v[4:5], v[4:5], 2, s[44:45]
	v_lshl_add_u64 v[4:5], s[48:49], 2, v[4:5]
	v_lshl_add_u64 v[4:5], v[4:5], 0, v[28:29]
	global_load_dwordx4 v[4:7], v[4:5], off nt
	v_cndmask_b32_e64 v8, 0, 1, s[52:53]
	v_cmp_ne_u32_e64 s[4:5], 1, v8
	s_andn2_b64 vcc, exec, s[52:53]
	s_cbranch_vccnz .LBB0_1948
.LBB0_1948:
	v_or_b32_e32 v36, 16, v34
	v_add_u32_e32 v8, s10, v36
	v_ashrrev_i32_e32 v9, 31, v8
	v_mul_lo_u32 v10, s50, v9
	v_mul_lo_u32 v11, s51, v8
	v_mad_u64_u32 v[8:9], s[14:15], s50, v8, 0
	v_add3_u32 v9, v9, v10, v11
	v_lshl_add_u64 v[8:9], v[8:9], 2, s[44:45]
	v_lshl_add_u64 v[8:9], s[48:49], 2, v[8:9]
	v_mov_b32_e32 v29, 0
	v_lshl_add_u64 v[8:9], v[8:9], 0, v[28:29]
	global_load_dwordx4 v[8:11], v[8:9], off nt
	s_and_b64 vcc, exec, s[4:5]
	s_cbranch_vccnz .LBB0_1950
.LBB0_1950:
	v_or_b32_e32 v37, 24, v34
	v_add_u32_e32 v12, s10, v37
	v_ashrrev_i32_e32 v13, 31, v12
	v_mul_lo_u32 v14, s50, v13
	v_mul_lo_u32 v15, s51, v12
	v_mad_u64_u32 v[12:13], s[14:15], s50, v12, 0
	v_add3_u32 v13, v13, v14, v15
	v_lshl_add_u64 v[12:13], v[12:13], 2, s[44:45]
	v_lshl_add_u64 v[12:13], s[48:49], 2, v[12:13]
	v_lshl_add_u64 v[12:13], v[12:13], 0, v[28:29]
	global_load_dwordx4 v[12:15], v[12:13], off nt
	s_and_b64 vcc, exec, s[4:5]
	s_cbranch_vccnz .LBB0_1952
.LBB0_1952:
	v_add3_u32 v16, s10, v34, 32
	v_ashrrev_i32_e32 v17, 31, v16
	v_mul_lo_u32 v18, s50, v17
	v_mul_lo_u32 v19, s51, v16
	v_mad_u64_u32 v[16:17], s[14:15], s50, v16, 0
	v_add3_u32 v17, v17, v18, v19
	v_lshl_add_u64 v[16:17], v[16:17], 2, s[44:45]
	v_lshl_add_u64 v[16:17], s[48:49], 2, v[16:17]
	v_mov_b32_e32 v29, 0
	v_lshl_add_u64 v[16:17], v[16:17], 0, v[28:29]
	global_load_dwordx4 v[16:19], v[16:17], off nt
	s_and_b64 vcc, exec, s[4:5]
	s_cbranch_vccnz .LBB0_1954
.LBB0_1954:
	v_add3_u32 v20, s10, v34, 40
	v_ashrrev_i32_e32 v21, 31, v20
	v_mul_lo_u32 v22, s50, v21
	v_mul_lo_u32 v23, s51, v20
	v_mad_u64_u32 v[20:21], s[14:15], s50, v20, 0
	v_add3_u32 v21, v21, v22, v23
	v_lshl_add_u64 v[20:21], v[20:21], 2, s[44:45]
	v_lshl_add_u64 v[20:21], s[48:49], 2, v[20:21]
	v_lshl_add_u64 v[20:21], v[20:21], 0, v[28:29]
	global_load_dwordx4 v[20:23], v[20:21], off nt
	s_and_b64 vcc, exec, s[4:5]
	s_cbranch_vccnz .LBB0_1956
.LBB0_1956:
	v_add3_u32 v24, s10, v34, 48
	v_ashrrev_i32_e32 v25, 31, v24
	v_mul_lo_u32 v26, s50, v25
	v_mul_lo_u32 v27, s51, v24
	v_mad_u64_u32 v[24:25], s[14:15], s50, v24, 0
	v_add3_u32 v25, v25, v26, v27
	v_lshl_add_u64 v[24:25], v[24:25], 2, s[44:45]
	v_lshl_add_u64 v[24:25], s[48:49], 2, v[24:25]
	v_mov_b32_e32 v29, 0
	v_lshl_add_u64 v[24:25], v[24:25], 0, v[28:29]
	global_load_dwordx4 v[24:27], v[24:25], off nt
	s_and_b64 vcc, exec, s[4:5]
	s_cbranch_vccnz .LBB0_1958

.LBB0_2103:
	v_lshrrev_b32_e32 v34, 3, v241
	v_add_u32_e32 v4, s10, v34
	v_lshlrev_b32_e32 v0, 2, v240
	v_ashrrev_i32_e32 v5, 31, v4
	v_and_b32_e32 v2, 28, v0
	v_mul_lo_u32 v3, s48, v5
	v_mul_lo_u32 v6, s49, v4
	v_mad_u64_u32 v[0:1], s[14:15], s48, v4, 0
	v_add3_u32 v1, v1, v3, v6
	v_lshl_add_u64 v[0:1], v[0:1], 2, s[42:43]
	s_ashr_i32 s47, s46, 31
	v_mov_b32_e32 v29, 0
	v_lshl_add_u64 v[0:1], s[46:47], 2, v[0:1]
	v_lshlrev_b32_e32 v28, 2, v2
	v_lshl_add_u64 v[0:1], v[0:1], 0, v[28:29]
	global_load_dwordx4 v[0:3], v[0:1], off nt
	s_cmp_lg_u64 s[4:5], 0
	s_cselect_b64 s[50:51], -1, 0
	s_cmp_eq_u64 s[4:5], 0
	v_lshl_add_u64 v[32:33], v[4:5], 2, s[4:5]
	s_cbranch_scc1 .LBB0_2105
.LBB0_2105:
	v_or_b32_e32 v35, 8, v34
	v_add_u32_e32 v4, s10, v35
	v_ashrrev_i32_e32 v5, 31, v4
	v_mul_lo_u32 v6, s48, v5
	v_mul_lo_u32 v7, s49, v4
	v_mad_u64_u32 v[4:5], s[4:5], s48, v4, 0
	v_add3_u32 v5, v5, v6, v7
	v_lshl_add_u64 v[4:5], v[4:5], 2, s[42:43]
	v_lshl_add_u64 v[4:5], s[46:47], 2, v[4:5]
	v_lshl_add_u64 v[4:5], v[4:5], 0, v[28:29]
	global_load_dwordx4 v[4:7], v[4:5], off nt
	v_cndmask_b32_e64 v8, 0, 1, s[50:51]
	v_cmp_ne_u32_e64 s[4:5], 1, v8
	s_andn2_b64 vcc, exec, s[50:51]
	s_cbranch_vccnz .LBB0_2107
.LBB0_2107:
	v_or_b32_e32 v36, 16, v34
	v_add_u32_e32 v8, s10, v36
	v_ashrrev_i32_e32 v9, 31, v8
	v_mul_lo_u32 v10, s48, v9
	v_mul_lo_u32 v11, s49, v8
	v_mad_u64_u32 v[8:9], s[14:15], s48, v8, 0
	v_add3_u32 v9, v9, v10, v11
	v_lshl_add_u64 v[8:9], v[8:9], 2, s[42:43]
	v_lshl_add_u64 v[8:9], s[46:47], 2, v[8:9]
	v_mov_b32_e32 v29, 0
	v_lshl_add_u64 v[8:9], v[8:9], 0, v[28:29]
	global_load_dwordx4 v[8:11], v[8:9], off nt
	s_and_b64 vcc, exec, s[4:5]
	s_cbranch_vccnz .LBB0_2109
.LBB0_2109:
	v_or_b32_e32 v37, 24, v34
	v_add_u32_e32 v12, s10, v37
	v_ashrrev_i32_e32 v13, 31, v12
	v_mul_lo_u32 v14, s48, v13
	v_mul_lo_u32 v15, s49, v12
	v_mad_u64_u32 v[12:13], s[14:15], s48, v12, 0
	v_add3_u32 v13, v13, v14, v15
	v_lshl_add_u64 v[12:13], v[12:13], 2, s[42:43]
	v_lshl_add_u64 v[12:13], s[46:47], 2, v[12:13]
	v_lshl_add_u64 v[12:13], v[12:13], 0, v[28:29]
	global_load_dwordx4 v[12:15], v[12:13], off nt
	s_and_b64 vcc, exec, s[4:5]
	s_cbranch_vccnz .LBB0_2111
.LBB0_2111:
	v_add3_u32 v16, s10, v34, 32
	v_ashrrev_i32_e32 v17, 31, v16
	v_mul_lo_u32 v18, s48, v17
	v_mul_lo_u32 v19, s49, v16
	v_mad_u64_u32 v[16:17], s[14:15], s48, v16, 0
	v_add3_u32 v17, v17, v18, v19
	v_lshl_add_u64 v[16:17], v[16:17], 2, s[42:43]
	v_lshl_add_u64 v[16:17], s[46:47], 2, v[16:17]
	v_mov_b32_e32 v29, 0
	v_lshl_add_u64 v[16:17], v[16:17], 0, v[28:29]
	global_load_dwordx4 v[16:19], v[16:17], off nt
	s_and_b64 vcc, exec, s[4:5]
	s_cbranch_vccnz .LBB0_2113
.LBB0_2113:
	v_add3_u32 v20, s10, v34, 40
	v_ashrrev_i32_e32 v21, 31, v20
	v_mul_lo_u32 v22, s48, v21
	v_mul_lo_u32 v23, s49, v20
	v_mad_u64_u32 v[20:21], s[14:15], s48, v20, 0
	v_add3_u32 v21, v21, v22, v23
	v_lshl_add_u64 v[20:21], v[20:21], 2, s[42:43]
	v_lshl_add_u64 v[20:21], s[46:47], 2, v[20:21]
	v_lshl_add_u64 v[20:21], v[20:21], 0, v[28:29]
	global_load_dwordx4 v[20:23], v[20:21], off nt
	s_and_b64 vcc, exec, s[4:5]
	s_cbranch_vccnz .LBB0_2115
.LBB0_2115:
	v_add3_u32 v24, s10, v34, 48
	v_ashrrev_i32_e32 v25, 31, v24
	v_mul_lo_u32 v26, s48, v25
	v_mul_lo_u32 v27, s49, v24
	v_mad_u64_u32 v[24:25], s[14:15], s48, v24, 0
	v_add3_u32 v25, v25, v26, v27
	v_lshl_add_u64 v[24:25], v[24:25], 2, s[42:43]
	v_lshl_add_u64 v[24:25], s[46:47], 2, v[24:25]
	v_mov_b32_e32 v29, 0
	v_lshl_add_u64 v[24:25], v[24:25], 0, v[28:29]
	global_load_dwordx4 v[24:27], v[24:25], off nt
	s_and_b64 vcc, exec, s[4:5]
	s_cbranch_vccnz .LBB0_2117
.LBB0_2117:
	v_add3_u32 v30, s10, v34, 56
	v_ashrrev_i32_e32 v31, 31, v30
	v_mul_lo_u32 v38, s48, v31
	v_mul_lo_u32 v39, s49, v30
	v_mad_u64_u32 v[30:31], s[14:15], s48, v30, 0
	v_add3_u32 v31, v31, v38, v39
	v_lshl_add_u64 v[30:31], v[30:31], 2, s[42:43]
	v_lshl_add_u64 v[30:31], s[46:47], 2, v[30:31]
	v_lshl_add_u64 v[28:29], v[30:31], 0, v[28:29]
	global_load_dwordx4 v[28:31], v[28:29], off nt
	s_and_b64 vcc, exec, s[4:5]
	s_cbranch_vccnz .LBB0_2119
	global_load_dword v90, v[32:33], off
	global_load_dword v92, v[32:33], off offset:32
	global_load_dword v94, v[32:33], off offset:64
	global_load_dword v96, v[32:33], off offset:96
	global_load_dword v98, v[32:33], off offset:128
	global_load_dword v100, v[32:33], off offset:160
	global_load_dword v102, v[32:33], off offset:192
	global_load_dword v104, v[32:33], off offset:224
	s_waitcnt vmcnt(0)
	v_pk_mul_f32 v[2:3], v[2:3], v[90:91] op_sel_hi:[1,0]
	v_pk_mul_f32 v[0:1], v[0:1], v[90:91] op_sel_hi:[1,0]
	v_pk_mul_f32 v[6:7], v[6:7], v[92:93] op_sel_hi:[1,0]
	v_pk_mul_f32 v[4:5], v[4:5], v[92:93] op_sel_hi:[1,0]
	v_pk_mul_f32 v[10:11], v[10:11], v[94:95] op_sel_hi:[1,0]
	v_pk_mul_f32 v[8:9], v[8:9], v[94:95] op_sel_hi:[1,0]
	v_pk_mul_f32 v[14:15], v[14:15], v[96:97] op_sel_hi:[1,0]
	v_pk_mul_f32 v[12:13], v[12:13], v[96:97] op_sel_hi:[1,0]
	v_pk_mul_f32 v[18:19], v[18:19], v[98:99] op_sel_hi:[1,0]
	v_pk_mul_f32 v[16:17], v[16:17], v[98:99] op_sel_hi:[1,0]
	v_pk_mul_f32 v[22:23], v[22:23], v[100:101] op_sel_hi:[1,0]
	v_pk_mul_f32 v[20:21], v[20:21], v[100:101] op_sel_hi:[1,0]
	v_pk_mul_f32 v[26:27], v[26:27], v[102:103] op_sel_hi:[1,0]
	v_pk_mul_f32 v[24:25], v[24:25], v[102:103] op_sel_hi:[1,0]
	v_pk_mul_f32 v[30:31], v[30:31], v[104:105] op_sel_hi:[1,0]
	v_pk_mul_f32 v[28:29], v[28:29], v[104:105] op_sel_hi:[1,0]

.LBB0_2246:
	v_lshrrev_b32_e32 v34, 3, v241
	v_add_u32_e32 v4, s10, v34
	v_lshlrev_b32_e32 v0, 2, v240
	v_ashrrev_i32_e32 v5, 31, v4
	v_and_b32_e32 v2, 28, v0
	v_mul_lo_u32 v3, s42, v5
	v_mul_lo_u32 v6, s43, v4
	v_mad_u64_u32 v[0:1], s[14:15], s42, v4, 0
	v_readlane_b32 s44, v254, 0
	v_add3_u32 v1, v1, v3, v6
	v_readlane_b32 s46, v254, 2
	v_readlane_b32 s47, v254, 3
	s_ashr_i32 s29, s28, 31
	v_mov_b32_e32 v29, 0
	v_lshl_add_u64 v[0:1], v[0:1], 2, s[46:47]
	v_lshl_add_u64 v[0:1], s[28:29], 2, v[0:1]
	v_lshlrev_b32_e32 v28, 2, v2
	v_lshl_add_u64 v[0:1], v[0:1], 0, v[28:29]
	global_load_dwordx4 v[0:3], v[0:1], off nt
	s_cmp_lg_u64 s[4:5], 0
	s_cselect_b64 s[14:15], -1, 0
	s_cmp_eq_u64 s[4:5], 0
	v_lshl_add_u64 v[32:33], v[4:5], 2, s[4:5]
	v_readlane_b32 s45, v254, 1
	v_readlane_b32 s48, v254, 4
	v_readlane_b32 s49, v254, 5
	v_readlane_b32 s50, v254, 6
	v_readlane_b32 s51, v254, 7
	s_cbranch_scc1 .LBB0_2248
.LBB0_2248:
	v_or_b32_e32 v35, 8, v34
	v_add_u32_e32 v4, s10, v35
	v_ashrrev_i32_e32 v5, 31, v4
	v_mul_lo_u32 v6, s42, v5
	v_mul_lo_u32 v7, s43, v4
	v_mad_u64_u32 v[4:5], s[4:5], s42, v4, 0
	v_readlane_b32 s44, v254, 0
	v_add3_u32 v5, v5, v6, v7
	v_readlane_b32 s46, v254, 2
	v_readlane_b32 s47, v254, 3
	v_cndmask_b32_e64 v8, 0, 1, s[14:15]
	v_cmp_ne_u32_e64 s[4:5], 1, v8
	v_lshl_add_u64 v[4:5], v[4:5], 2, s[46:47]
	v_lshl_add_u64 v[4:5], s[28:29], 2, v[4:5]
	v_lshl_add_u64 v[4:5], v[4:5], 0, v[28:29]
	global_load_dwordx4 v[4:7], v[4:5], off nt
	s_andn2_b64 vcc, exec, s[14:15]
	v_readlane_b32 s45, v254, 1
	v_readlane_b32 s48, v254, 4
	v_readlane_b32 s49, v254, 5
	v_readlane_b32 s50, v254, 6
	v_readlane_b32 s51, v254, 7
	s_cbranch_vccnz .LBB0_2250
.LBB0_2250:
	v_or_b32_e32 v36, 16, v34
	v_add_u32_e32 v8, s10, v36
	v_ashrrev_i32_e32 v9, 31, v8
	v_mul_lo_u32 v10, s42, v9
	v_mul_lo_u32 v11, s43, v8
	v_mad_u64_u32 v[8:9], s[14:15], s42, v8, 0
	v_readlane_b32 s44, v254, 0
	v_add3_u32 v9, v9, v10, v11
	v_readlane_b32 s46, v254, 2
	v_readlane_b32 s47, v254, 3
	v_mov_b32_e32 v29, 0
	s_and_b64 vcc, exec, s[4:5]
	v_lshl_add_u64 v[8:9], v[8:9], 2, s[46:47]
	v_lshl_add_u64 v[8:9], s[28:29], 2, v[8:9]
	v_lshl_add_u64 v[8:9], v[8:9], 0, v[28:29]
	global_load_dwordx4 v[8:11], v[8:9], off nt
	v_readlane_b32 s45, v254, 1
	v_readlane_b32 s48, v254, 4
	v_readlane_b32 s49, v254, 5
	v_readlane_b32 s50, v254, 6
	v_readlane_b32 s51, v254, 7
	s_cbranch_vccnz .LBB0_2252
.LBB0_2252:
	v_or_b32_e32 v37, 24, v34
	v_add_u32_e32 v12, s10, v37
	v_ashrrev_i32_e32 v13, 31, v12
	v_mul_lo_u32 v14, s42, v13
	v_mul_lo_u32 v15, s43, v12
	v_mad_u64_u32 v[12:13], s[14:15], s42, v12, 0
	v_readlane_b32 s44, v254, 0
	v_add3_u32 v13, v13, v14, v15
	v_readlane_b32 s46, v254, 2
	v_readlane_b32 s47, v254, 3
	s_and_b64 vcc, exec, s[4:5]
	v_readlane_b32 s45, v254, 1
	v_lshl_add_u64 v[12:13], v[12:13], 2, s[46:47]
	v_lshl_add_u64 v[12:13], s[28:29], 2, v[12:13]
	v_lshl_add_u64 v[12:13], v[12:13], 0, v[28:29]
	global_load_dwordx4 v[12:15], v[12:13], off nt
	v_readlane_b32 s48, v254, 4
	v_readlane_b32 s49, v254, 5
	v_readlane_b32 s50, v254, 6
	v_readlane_b32 s51, v254, 7
	s_cbranch_vccnz .LBB0_2254
.LBB0_2254:
	v_add3_u32 v16, s10, v34, 32
	v_ashrrev_i32_e32 v17, 31, v16
	v_mul_lo_u32 v18, s42, v17
	v_mul_lo_u32 v19, s43, v16
	v_mad_u64_u32 v[16:17], s[14:15], s42, v16, 0
	v_readlane_b32 s44, v254, 0
	v_add3_u32 v17, v17, v18, v19
	v_readlane_b32 s46, v254, 2
	v_readlane_b32 s47, v254, 3
	v_mov_b32_e32 v29, 0
	s_and_b64 vcc, exec, s[4:5]
	v_lshl_add_u64 v[16:17], v[16:17], 2, s[46:47]
	v_lshl_add_u64 v[16:17], s[28:29], 2, v[16:17]
	v_lshl_add_u64 v[16:17], v[16:17], 0, v[28:29]
	global_load_dwordx4 v[16:19], v[16:17], off nt
	v_readlane_b32 s45, v254, 1
	v_readlane_b32 s48, v254, 4
	v_readlane_b32 s49, v254, 5
	v_readlane_b32 s50, v254, 6
	v_readlane_b32 s51, v254, 7
	s_cbranch_vccnz .LBB0_2256
.LBB0_2256:
	v_add3_u32 v20, s10, v34, 40
	v_ashrrev_i32_e32 v21, 31, v20
	v_mul_lo_u32 v22, s42, v21
	v_mul_lo_u32 v23, s43, v20
	v_mad_u64_u32 v[20:21], s[14:15], s42, v20, 0
	v_readlane_b32 s44, v254, 0
	v_add3_u32 v21, v21, v22, v23
	v_readlane_b32 s46, v254, 2
	v_readlane_b32 s47, v254, 3
	s_and_b64 vcc, exec, s[4:5]
	v_readlane_b32 s45, v254, 1
	v_lshl_add_u64 v[20:21], v[20:21], 2, s[46:47]
	v_lshl_add_u64 v[20:21], s[28:29], 2, v[20:21]
	v_lshl_add_u64 v[20:21], v[20:21], 0, v[28:29]
	global_load_dwordx4 v[20:23], v[20:21], off nt
	v_readlane_b32 s48, v254, 4
	v_readlane_b32 s49, v254, 5
	v_readlane_b32 s50, v254, 6
	v_readlane_b32 s51, v254, 7
	s_cbranch_vccnz .LBB0_2258
.LBB0_2258:
	v_add3_u32 v24, s10, v34, 48
	v_ashrrev_i32_e32 v25, 31, v24
	v_mul_lo_u32 v26, s42, v25
	v_mul_lo_u32 v27, s43, v24
	v_mad_u64_u32 v[24:25], s[14:15], s42, v24, 0
	v_readlane_b32 s44, v254, 0
	v_add3_u32 v25, v25, v26, v27
	v_readlane_b32 s46, v254, 2
	v_readlane_b32 s47, v254, 3
	v_mov_b32_e32 v29, 0
	s_and_b64 vcc, exec, s[4:5]
	v_lshl_add_u64 v[24:25], v[24:25], 2, s[46:47]
	v_lshl_add_u64 v[24:25], s[28:29], 2, v[24:25]
	v_lshl_add_u64 v[24:25], v[24:25], 0, v[28:29]
	global_load_dwordx4 v[24:27], v[24:25], off nt
	v_readlane_b32 s45, v254, 1
	v_readlane_b32 s48, v254, 4
	v_readlane_b32 s49, v254, 5
	v_readlane_b32 s50, v254, 6
	v_readlane_b32 s51, v254, 7
	s_cbranch_vccnz .LBB0_2260
.LBB0_2260:
	v_add3_u32 v30, s10, v34, 56
	v_ashrrev_i32_e32 v31, 31, v30
	v_mul_lo_u32 v38, s42, v31
	v_mul_lo_u32 v39, s43, v30
	v_mad_u64_u32 v[30:31], s[14:15], s42, v30, 0
	v_readlane_b32 s36, v254, 0
	v_add3_u32 v31, v31, v38, v39
	v_readlane_b32 s38, v254, 2
	v_readlane_b32 s39, v254, 3
	s_and_b64 vcc, exec, s[4:5]
	v_readlane_b32 s37, v254, 1
	v_lshl_add_u64 v[30:31], v[30:31], 2, s[38:39]
	v_lshl_add_u64 v[30:31], s[28:29], 2, v[30:31]
	v_lshl_add_u64 v[28:29], v[30:31], 0, v[28:29]
	global_load_dwordx4 v[28:31], v[28:29], off nt
	v_readlane_b32 s40, v254, 4
	v_readlane_b32 s41, v254, 5
	v_readlane_b32 s42, v254, 6
	v_readlane_b32 s43, v254, 7
	s_cbranch_vccnz .LBB0_2262
	global_load_dword v90, v[32:33], off
	global_load_dword v92, v[32:33], off offset:32
	global_load_dword v94, v[32:33], off offset:64
	global_load_dword v96, v[32:33], off offset:96
	global_load_dword v98, v[32:33], off offset:128
	global_load_dword v100, v[32:33], off offset:160
	global_load_dword v102, v[32:33], off offset:192
	global_load_dword v104, v[32:33], off offset:224
	s_waitcnt vmcnt(0)
	v_pk_mul_f32 v[2:3], v[2:3], v[90:91] op_sel_hi:[1,0]
	v_pk_mul_f32 v[0:1], v[0:1], v[90:91] op_sel_hi:[1,0]
	v_pk_mul_f32 v[6:7], v[6:7], v[92:93] op_sel_hi:[1,0]
	v_pk_mul_f32 v[4:5], v[4:5], v[92:93] op_sel_hi:[1,0]
	v_pk_mul_f32 v[10:11], v[10:11], v[94:95] op_sel_hi:[1,0]
	v_pk_mul_f32 v[8:9], v[8:9], v[94:95] op_sel_hi:[1,0]
	v_pk_mul_f32 v[14:15], v[14:15], v[96:97] op_sel_hi:[1,0]
	v_pk_mul_f32 v[12:13], v[12:13], v[96:97] op_sel_hi:[1,0]
	v_pk_mul_f32 v[18:19], v[18:19], v[98:99] op_sel_hi:[1,0]
	v_pk_mul_f32 v[16:17], v[16:17], v[98:99] op_sel_hi:[1,0]
	v_pk_mul_f32 v[22:23], v[22:23], v[100:101] op_sel_hi:[1,0]
	v_pk_mul_f32 v[20:21], v[20:21], v[100:101] op_sel_hi:[1,0]
	v_pk_mul_f32 v[26:27], v[26:27], v[102:103] op_sel_hi:[1,0]
	v_pk_mul_f32 v[24:25], v[24:25], v[102:103] op_sel_hi:[1,0]
	v_pk_mul_f32 v[30:31], v[30:31], v[104:105] op_sel_hi:[1,0]
	v_pk_mul_f32 v[28:29], v[28:29], v[104:105] op_sel_hi:[1,0]
